# hand-written sample-row mini GEMMs (256 WGs, 8-slot load ring) at all four sites
# speedup vs baseline: 1.0305x; 1.0305x over previous
; #define LAS __attribute__((address_space(3)))
; __device__ __forceinline__ f32x4 mini_acc(const bf16_t* A, int lda, const bf16_t* Bt, int ldb, int K, int n0, int wave, int fr, int fq, LAS unsigned char* lds) {
;     asm volatile("" : "+s"(lda), "+s"(ldb));
;     const int lane = fq * 16 + fr, ks = K >> 3;
;     const bf16_t* ap = A + (size_t)(MP + fr) * lda + wave * ks + 8 * fq;
;     const bf16_t* bp = Bt + (size_t)(n0 + fr) * ldb + wave * ks + 8 * fq;
;     f32x4 acc[8];
; #pragma unroll
;     for (int m = 0; m < 8; ++m) acc[m] = (f32x4){0.f, 0.f, 0.f, 0.f};
;     for (int k = 0; k < ks; k += 64) {
;         const bool two = (k + 32 < ks);
;         bf16x8 bq[2], aq[2][8];
;         bq[0] = *(const bf16x8*)(bp + k);
; #pragma unroll
;         for (int m = 0; m < 8; ++m) aq[0][m] = *(const bf16x8*)(ap + (size_t)(16 * m) * lda + k);
;         if (two) { bq[1] = *(const bf16x8*)(bp + k + 32);
; #pragma unroll
;             for (int m = 0; m < 8; ++m) aq[1][m] = *(const bf16x8*)(ap + (size_t)(16 * m) * lda + k + 32); }
; #pragma unroll
;         for (int m = 0; m < 8; ++m) acc[m] = __builtin_amdgcn_mfma_f32_16x16x32_bf16(bq[0], aq[0][m], acc[m], 0, 0, 0);
;         if (two) {
; #pragma unroll
;             for (int m = 0; m < 8; ++m) acc[m] = __builtin_amdgcn_mfma_f32_16x16x32_bf16(bq[1], aq[1][m], acc[m], 0, 0, 0); }
; __global__ void __launch_bounds__(512, 2) mega(Params p) {
;     ...
;         {
;             const int tid = opaque_tid(wave_s), lane = tid & 63, wave = tid >> 6, fr = lane & 15, fq = lane >> 4;
;             for (int nt = bx; nt < 128; nt += G) { const int n0 = nt * 16; const f32x4 z4 = (f32x4){0.f, 0.f, 0.f, 0.f};
;                 const f32x4 a1 = mini_acc((const bf16_t*)(ws + WS_POOLOUT), 1024, (const bf16_t*)(ws + WS_WPU), 1024, 1024, n0, wave, fr, fq, lds);
;                 const f32x4 a2 = mini_acc((const bf16_t*)(ws + WS_GDNOUT), DM, (const bf16_t*)(ws + WS_WGU), DM, DM, n0, wave, fr, fq, lds);
;                 const size_t r = MP + 16 * wave + fr; const int c = n0 + 4 * fq;
;                 const f32x4 gp = bf4_to_f32(*(const u32x2*)((const bf16_t*)(ws + WS_GATES) + r * NG + c)), gg = bf4_to_f32(*(const u32x2*)((const bf16_t*)(ws + WS_GATES) + r * NG + 2048 + c));
;                 *(u32x2*)((bf16_t*)(ws + WS_MERGED) + r * DM + c) = f32_to_bf4(gp * a1 + gg * a2); }
.LBB0_1047:
	s_mov_b64 exec, -1
	s_cmpk_gt_u32 s2, 0xff
	s_cbranch_scc1 .Lmini4_done
	v_mbcnt_lo_u32_b32 v0, -1, 0
	v_mbcnt_hi_u32_b32 v0, -1, v0
	v_and_b32_e32 v1, 15, v0
	v_lshrrev_b32_e32 v2, 4, v0
	s_lshr_b32 s84, s24, 6
	s_and_b32 s85, s2, 7
	s_lshr_b32 s86, s2, 4
	s_lshl_b32 s86, s86, 3
	s_or_b32 s85, s85, s86
	s_lshl_b32 s85, s85, 4
	s_bfe_u32 s86, s2, 0x10003
	s_lshl_b32 s86, s86, 6
	s_addk_i32 s86, 0x2000
	v_lshlrev_b32_e32 v20, 4, v0
	s_lshl_b32 s87, s84, 12
	v_add_u32_e32 v20, s87, v20
	v_lshlrev_b32_e32 v21, 4, v0
	s_lshl_b32 s87, s84, 10
	v_add_u32_e32 v21, s87, v21
	s_add_u32 s90, s22, 0x752a000
	s_addc_u32 s91, s23, 0
	s_add_u32 s92, s22, 0x80000
	s_addc_u32 s93, s23, 0
	s_mul_i32 s87, s84, 0x100
	v_lshl_add_u32 v3, v2, 4, s87
	v_add_u32_e32 v4, s86, v1
	s_mov_b32 s88, 0x800
	v_mul_lo_u32 v5, v4, s88
	v_add_u32_e32 v10, v5, v3
	v_add_u32_e32 v11, 0x8000, v10
	v_add_u32_e32 v12, 0x10000, v10
	v_add_u32_e32 v13, 0x18000, v10
	v_add_u32_e32 v4, s85, v1
	s_mov_b32 s88, 0x800
	v_mul_lo_u32 v5, v4, s88
	v_add_u32_e32 v14, v5, v3
	s_add_u32 s94, s22, 0x85aa000
	s_addc_u32 s95, s23, 0
	s_add_u32 s96, s22, 0x480000
	s_addc_u32 s97, s23, 0
	s_mul_i32 s87, s84, 0x200
	v_lshl_add_u32 v3, v2, 4, s87
	v_add_u32_e32 v4, s86, v1
	s_mov_b32 s88, 0x1000
	v_mul_lo_u32 v5, v4, s88
	v_add_u32_e32 v15, v5, v3
	v_add_u32_e32 v16, 0x10000, v15
	v_add_u32_e32 v17, 0x20000, v15
	v_add_u32_e32 v18, 0x30000, v15
	v_add_u32_e32 v4, s85, v1
	s_mov_b32 s88, 0x1000
	v_mul_lo_u32 v5, v4, s88
	v_add_u32_e32 v19, v5, v3
	v_mov_b32_e32 v32, 0
	v_mov_b32_e32 v33, 0
	v_mov_b32_e32 v34, 0
	v_mov_b32_e32 v35, 0
	v_mov_b32_e32 v36, 0
	v_mov_b32_e32 v37, 0
	v_mov_b32_e32 v38, 0
	v_mov_b32_e32 v39, 0
	v_mov_b32_e32 v40, 0
	v_mov_b32_e32 v41, 0
	v_mov_b32_e32 v42, 0
	v_mov_b32_e32 v43, 0
	v_mov_b32_e32 v44, 0
	v_mov_b32_e32 v45, 0
	v_mov_b32_e32 v46, 0
	v_mov_b32_e32 v47, 0
	v_mov_b32_e32 v48, 0
	v_mov_b32_e32 v49, 0
	v_mov_b32_e32 v50, 0
	v_mov_b32_e32 v51, 0
	v_mov_b32_e32 v52, 0
	v_mov_b32_e32 v53, 0
	v_mov_b32_e32 v54, 0
	v_mov_b32_e32 v55, 0
	v_mov_b32_e32 v56, 0
	v_mov_b32_e32 v57, 0
	v_mov_b32_e32 v58, 0
	v_mov_b32_e32 v59, 0
	v_mov_b32_e32 v60, 0
	v_mov_b32_e32 v61, 0
	v_mov_b32_e32 v62, 0
	v_mov_b32_e32 v63, 0
	s_cmp_gt_u32 s84, 3
	s_cbranch_scc1 .Lmini4_noepi
	s_lshl_b32 s87, s84, 4
	s_add_i32 s87, s87, s86
	v_add_u32_e32 v4, s87, v1
	v_lshl_add_u32 v5, v2, 2, s85
	v_lshlrev_b32_e32 v7, 12, v4
	v_lshl_add_u32 v7, v5, 1, v7
	s_add_u32 s8, s22, 0x13b2a000
	s_addc_u32 s9, s23, 0
	s_add_u32 s10, s22, 0x13b2b000
	s_addc_u32 s11, s23, 0
	s_add_u32 s12, s22, 0xe8aa000
	s_addc_u32 s13, s23, 0
	v_lshlrev_b32_e32 v6, 13, v4
	v_lshl_add_u32 v6, v5, 1, v6
	global_load_dwordx2 v[224:225], v6, s[8:9]
	global_load_dwordx2 v[226:227], v6, s[10:11]
.Lmini4_noepi:
	global_load_dwordx4 v[64:67], v14, s[92:93]
	global_load_dwordx4 v[68:71], v10, s[90:91]
	global_load_dwordx4 v[72:75], v11, s[90:91]
	global_load_dwordx4 v[76:79], v12, s[90:91]
	global_load_dwordx4 v[80:83], v13, s[90:91]
	global_load_dwordx4 v[84:87], v14, s[92:93] offset:64
	global_load_dwordx4 v[88:91], v10, s[90:91] offset:64
	global_load_dwordx4 v[92:95], v11, s[90:91] offset:64
	global_load_dwordx4 v[96:99], v12, s[90:91] offset:64
	global_load_dwordx4 v[100:103], v13, s[90:91] offset:64
	global_load_dwordx4 v[104:107], v14, s[92:93] offset:128
	global_load_dwordx4 v[108:111], v10, s[90:91] offset:128
	global_load_dwordx4 v[112:115], v11, s[90:91] offset:128
	global_load_dwordx4 v[116:119], v12, s[90:91] offset:128
	global_load_dwordx4 v[120:123], v13, s[90:91] offset:128
	global_load_dwordx4 v[124:127], v14, s[92:93] offset:192
	global_load_dwordx4 v[128:131], v10, s[90:91] offset:192
	global_load_dwordx4 v[132:135], v11, s[90:91] offset:192
	global_load_dwordx4 v[136:139], v12, s[90:91] offset:192
	global_load_dwordx4 v[140:143], v13, s[90:91] offset:192
	global_load_dwordx4 v[144:147], v19, s[96:97]
	global_load_dwordx4 v[148:151], v15, s[94:95]
	global_load_dwordx4 v[152:155], v16, s[94:95]
	global_load_dwordx4 v[156:159], v17, s[94:95]
	global_load_dwordx4 v[160:163], v18, s[94:95]
	global_load_dwordx4 v[164:167], v19, s[96:97] offset:64
	global_load_dwordx4 v[168:171], v15, s[94:95] offset:64
	global_load_dwordx4 v[172:175], v16, s[94:95] offset:64
	global_load_dwordx4 v[176:179], v17, s[94:95] offset:64
	global_load_dwordx4 v[180:183], v18, s[94:95] offset:64
	global_load_dwordx4 v[184:187], v19, s[96:97] offset:128
	global_load_dwordx4 v[188:191], v15, s[94:95] offset:128
	global_load_dwordx4 v[192:195], v16, s[94:95] offset:128
	global_load_dwordx4 v[196:199], v17, s[94:95] offset:128
	global_load_dwordx4 v[200:203], v18, s[94:95] offset:128
	global_load_dwordx4 v[204:207], v19, s[96:97] offset:192
	global_load_dwordx4 v[208:211], v15, s[94:95] offset:192
	global_load_dwordx4 v[212:215], v16, s[94:95] offset:192
	global_load_dwordx4 v[216:219], v17, s[94:95] offset:192
	global_load_dwordx4 v[220:223], v18, s[94:95] offset:192
	s_waitcnt vmcnt(35)
	v_mfma_f32_16x16x32_bf16 v[32:35], v[64:67], v[68:71], v[32:35]
	v_mfma_f32_16x16x32_bf16 v[36:39], v[64:67], v[72:75], v[36:39]
	v_mfma_f32_16x16x32_bf16 v[40:43], v[64:67], v[76:79], v[40:43]
	v_mfma_f32_16x16x32_bf16 v[44:47], v[64:67], v[80:83], v[44:47]
	global_load_dwordx4 v[64:67], v19, s[96:97] offset:256
	global_load_dwordx4 v[68:71], v15, s[94:95] offset:256
	global_load_dwordx4 v[72:75], v16, s[94:95] offset:256
	global_load_dwordx4 v[76:79], v17, s[94:95] offset:256
	global_load_dwordx4 v[80:83], v18, s[94:95] offset:256
	s_waitcnt vmcnt(35)
; #define LAS __attribute__((address_space(3)))
; #define BAR_LDS() do { asm volatile("s_waitcnt lgkmcnt(0)" ::: "memory"); __builtin_amdgcn_s_barrier(); asm volatile("" ::: "memory"); } while (0)
; __device__ __forceinline__ f32x4 mini_acc(const bf16_t* A, int lda, const bf16_t* Bt, int ldb, int K, int n0, int wave, int fr, int fq, LAS unsigned char* lds) {
;     ...
;     for (int k = 0; k < ks; k += 64) {
;         const bool two = (k + 32 < ks);
;         bf16x8 bq[2], aq[2][8];
;         bq[0] = *(const bf16x8*)(bp + k);
; #pragma unroll
;         for (int m = 0; m < 8; ++m) aq[0][m] = *(const bf16x8*)(ap + (size_t)(16 * m) * lda + k);
;         if (two) { bq[1] = *(const bf16x8*)(bp + k + 32);
; #pragma unroll
;             for (int m = 0; m < 8; ++m) aq[1][m] = *(const bf16x8*)(ap + (size_t)(16 * m) * lda + k + 32); }
; #pragma unroll
;         for (int m = 0; m < 8; ++m) acc[m] = __builtin_amdgcn_mfma_f32_16x16x32_bf16(bq[0], aq[0][m], acc[m], 0, 0, 0);
;         if (two) {
; #pragma unroll
;             for (int m = 0; m < 8; ++m) acc[m] = __builtin_amdgcn_mfma_f32_16x16x32_bf16(bq[1], aq[1][m], acc[m], 0, 0, 0); }
;     }
;     LAS f32x4* RED = (LAS f32x4*)lds;
; #pragma unroll
;     for (int m = 0; m < 8; ++m) RED[(wave * 8 + m) * 64 + lane] = acc[m];
;     BAR_LDS();
	v_mfma_f32_16x16x32_bf16 v[32:35], v[84:87], v[88:91], v[32:35]
	v_mfma_f32_16x16x32_bf16 v[36:39], v[84:87], v[92:95], v[36:39]
	v_mfma_f32_16x16x32_bf16 v[40:43], v[84:87], v[96:99], v[40:43]
	v_mfma_f32_16x16x32_bf16 v[44:47], v[84:87], v[100:103], v[44:47]
	global_load_dwordx4 v[84:87], v19, s[96:97] offset:320
	global_load_dwordx4 v[88:91], v15, s[94:95] offset:320
	global_load_dwordx4 v[92:95], v16, s[94:95] offset:320
	global_load_dwordx4 v[96:99], v17, s[94:95] offset:320
	global_load_dwordx4 v[100:103], v18, s[94:95] offset:320
	s_waitcnt vmcnt(35)
	v_mfma_f32_16x16x32_bf16 v[32:35], v[104:107], v[108:111], v[32:35]
	v_mfma_f32_16x16x32_bf16 v[36:39], v[104:107], v[112:115], v[36:39]
	v_mfma_f32_16x16x32_bf16 v[40:43], v[104:107], v[116:119], v[40:43]
	v_mfma_f32_16x16x32_bf16 v[44:47], v[104:107], v[120:123], v[44:47]
	global_load_dwordx4 v[104:107], v19, s[96:97] offset:384
	global_load_dwordx4 v[108:111], v15, s[94:95] offset:384
	global_load_dwordx4 v[112:115], v16, s[94:95] offset:384
	global_load_dwordx4 v[116:119], v17, s[94:95] offset:384
	global_load_dwordx4 v[120:123], v18, s[94:95] offset:384
	s_waitcnt vmcnt(35)
	v_mfma_f32_16x16x32_bf16 v[32:35], v[124:127], v[128:131], v[32:35]
	v_mfma_f32_16x16x32_bf16 v[36:39], v[124:127], v[132:135], v[36:39]
	v_mfma_f32_16x16x32_bf16 v[40:43], v[124:127], v[136:139], v[40:43]
	v_mfma_f32_16x16x32_bf16 v[44:47], v[124:127], v[140:143], v[44:47]
	global_load_dwordx4 v[124:127], v19, s[96:97] offset:448
	global_load_dwordx4 v[128:131], v15, s[94:95] offset:448
	global_load_dwordx4 v[132:135], v16, s[94:95] offset:448
	global_load_dwordx4 v[136:139], v17, s[94:95] offset:448
	global_load_dwordx4 v[140:143], v18, s[94:95] offset:448
	s_waitcnt vmcnt(35)
	v_mfma_f32_16x16x32_bf16 v[48:51], v[144:147], v[148:151], v[48:51]
	v_mfma_f32_16x16x32_bf16 v[52:55], v[144:147], v[152:155], v[52:55]
	v_mfma_f32_16x16x32_bf16 v[56:59], v[144:147], v[156:159], v[56:59]
	v_mfma_f32_16x16x32_bf16 v[60:63], v[144:147], v[160:163], v[60:63]
	s_waitcnt vmcnt(30)
	v_mfma_f32_16x16x32_bf16 v[48:51], v[164:167], v[168:171], v[48:51]
	v_mfma_f32_16x16x32_bf16 v[52:55], v[164:167], v[172:175], v[52:55]
	v_mfma_f32_16x16x32_bf16 v[56:59], v[164:167], v[176:179], v[56:59]
	v_mfma_f32_16x16x32_bf16 v[60:63], v[164:167], v[180:183], v[60:63]
	s_waitcnt vmcnt(25)
	v_mfma_f32_16x16x32_bf16 v[48:51], v[184:187], v[188:191], v[48:51]
	v_mfma_f32_16x16x32_bf16 v[52:55], v[184:187], v[192:195], v[52:55]
	v_mfma_f32_16x16x32_bf16 v[56:59], v[184:187], v[196:199], v[56:59]
	v_mfma_f32_16x16x32_bf16 v[60:63], v[184:187], v[200:203], v[60:63]
	s_waitcnt vmcnt(20)
	v_mfma_f32_16x16x32_bf16 v[48:51], v[204:207], v[208:211], v[48:51]
	v_mfma_f32_16x16x32_bf16 v[52:55], v[204:207], v[212:215], v[52:55]
	v_mfma_f32_16x16x32_bf16 v[56:59], v[204:207], v[216:219], v[56:59]
	v_mfma_f32_16x16x32_bf16 v[60:63], v[204:207], v[220:223], v[60:63]
	s_waitcnt vmcnt(15)
	v_mfma_f32_16x16x32_bf16 v[48:51], v[64:67], v[68:71], v[48:51]
	v_mfma_f32_16x16x32_bf16 v[52:55], v[64:67], v[72:75], v[52:55]
	v_mfma_f32_16x16x32_bf16 v[56:59], v[64:67], v[76:79], v[56:59]
	v_mfma_f32_16x16x32_bf16 v[60:63], v[64:67], v[80:83], v[60:63]
	s_waitcnt vmcnt(10)
	v_mfma_f32_16x16x32_bf16 v[48:51], v[84:87], v[88:91], v[48:51]
	v_mfma_f32_16x16x32_bf16 v[52:55], v[84:87], v[92:95], v[52:55]
	v_mfma_f32_16x16x32_bf16 v[56:59], v[84:87], v[96:99], v[56:59]
	v_mfma_f32_16x16x32_bf16 v[60:63], v[84:87], v[100:103], v[60:63]
	s_waitcnt vmcnt(5)
	v_mfma_f32_16x16x32_bf16 v[48:51], v[104:107], v[108:111], v[48:51]
	v_mfma_f32_16x16x32_bf16 v[52:55], v[104:107], v[112:115], v[52:55]
	v_mfma_f32_16x16x32_bf16 v[56:59], v[104:107], v[116:119], v[56:59]
	v_mfma_f32_16x16x32_bf16 v[60:63], v[104:107], v[120:123], v[60:63]
	s_waitcnt vmcnt(0)
	v_mfma_f32_16x16x32_bf16 v[48:51], v[124:127], v[128:131], v[48:51]
	v_mfma_f32_16x16x32_bf16 v[52:55], v[124:127], v[132:135], v[52:55]
	v_mfma_f32_16x16x32_bf16 v[56:59], v[124:127], v[136:139], v[56:59]
	v_mfma_f32_16x16x32_bf16 v[60:63], v[124:127], v[140:143], v[60:63]
	s_nop 7
	s_nop 3
	ds_write_b128 v20, v[32:35]
	ds_write_b128 v20, v[36:39] offset:1024
	ds_write_b128 v20, v[40:43] offset:2048
	ds_write_b128 v20, v[44:47] offset:3072
	ds_write_b128 v20, v[48:51] offset:32768
	ds_write_b128 v20, v[52:55] offset:33792
	ds_write_b128 v20, v[56:59] offset:34816
	ds_write_b128 v20, v[60:63] offset:35840
	s_waitcnt lgkmcnt(0)
	s_barrier
	s_cmp_gt_u32 s84, 3
	s_cbranch_scc1 .Lmini4_done
; __device__ __forceinline__ f32x4 bf4_to_f32(u32x2 w) { return (f32x4){bflo(w.x), bfhi(w.x), bflo(w.y), bfhi(w.y)}; }
; __device__ __forceinline__ u32x2 f32_to_bf4(f32x4 v) { u32x2 w; w.x = pk2(v[0], v[1]); w.y = pk2(v[2], v[3]); return w; }
; __device__ __forceinline__ f32x4 mini_acc(const bf16_t* A, int lda, const bf16_t* Bt, int ldb, int K, int n0, int wave, int fr, int fq, LAS unsigned char* lds) {
;     ...
;     f32x4 r = (f32x4){0.f, 0.f, 0.f, 0.f};
; #pragma unroll
;     for (int w2 = 0; w2 < 8; ++w2) r += RED[(w2 * 8 + wave) * 64 + lane];
; __global__ void __launch_bounds__(512, 2) mega(Params p) {
;     ...
;                 const size_t r = MP + 16 * wave + fr; const int c = n0 + 4 * fq;
;                 const f32x4 gp = bf4_to_f32(*(const u32x2*)((const bf16_t*)(ws + WS_GATES) + r * NG + c)), gg = bf4_to_f32(*(const u32x2*)((const bf16_t*)(ws + WS_GATES) + r * NG + 2048 + c));
;                 *(u32x2*)((bf16_t*)(ws + WS_MERGED) + r * DM + c) = f32_to_bf4(gp * a1 + gg * a2); }
	ds_read_b128 v[64:67], v21
	ds_read_b128 v[68:71], v21 offset:4096
	ds_read_b128 v[72:75], v21 offset:8192
	ds_read_b128 v[76:79], v21 offset:12288
	ds_read_b128 v[80:83], v21 offset:16384
	ds_read_b128 v[84:87], v21 offset:20480
	ds_read_b128 v[88:91], v21 offset:24576
	ds_read_b128 v[92:95], v21 offset:28672
	ds_read_b128 v[96:99], v21 offset:32768
	ds_read_b128 v[100:103], v21 offset:36864
	ds_read_b128 v[104:107], v21 offset:40960
	ds_read_b128 v[108:111], v21 offset:45056
	ds_read_b128 v[112:115], v21 offset:49152
	ds_read_b128 v[116:119], v21 offset:53248
	ds_read_b128 v[120:123], v21 offset:57344
	ds_read_b128 v[124:127], v21 offset:61440
	s_waitcnt vmcnt(0) lgkmcnt(0)
	v_add_f32_e32 v64, v64, v68
	v_add_f32_e32 v65, v65, v69
	v_add_f32_e32 v66, v66, v70
	v_add_f32_e32 v67, v67, v71
	v_add_f32_e32 v64, v64, v72
	v_add_f32_e32 v65, v65, v73
	v_add_f32_e32 v66, v66, v74
	v_add_f32_e32 v67, v67, v75
	v_add_f32_e32 v64, v64, v76
	v_add_f32_e32 v65, v65, v77
	v_add_f32_e32 v66, v66, v78
	v_add_f32_e32 v67, v67, v79
	v_add_f32_e32 v64, v64, v80
	v_add_f32_e32 v65, v65, v81
	v_add_f32_e32 v66, v66, v82
	v_add_f32_e32 v67, v67, v83
	v_add_f32_e32 v64, v64, v84
	v_add_f32_e32 v65, v65, v85
	v_add_f32_e32 v66, v66, v86
	v_add_f32_e32 v67, v67, v87
	v_add_f32_e32 v64, v64, v88
	v_add_f32_e32 v65, v65, v89
	v_add_f32_e32 v66, v66, v90
	v_add_f32_e32 v67, v67, v91
	v_add_f32_e32 v64, v64, v92
	v_add_f32_e32 v65, v65, v93
	v_add_f32_e32 v66, v66, v94
	v_add_f32_e32 v67, v67, v95
	v_add_f32_e32 v96, v96, v100
	v_add_f32_e32 v97, v97, v101
	v_add_f32_e32 v98, v98, v102
	v_add_f32_e32 v99, v99, v103
	v_add_f32_e32 v96, v96, v104
	v_add_f32_e32 v97, v97, v105
	v_add_f32_e32 v98, v98, v106
	v_add_f32_e32 v99, v99, v107
	v_add_f32_e32 v96, v96, v108
	v_add_f32_e32 v97, v97, v109
	v_add_f32_e32 v98, v98, v110
	v_add_f32_e32 v99, v99, v111
	v_add_f32_e32 v96, v96, v112
	v_add_f32_e32 v97, v97, v113
	v_add_f32_e32 v98, v98, v114
	v_add_f32_e32 v99, v99, v115
	v_add_f32_e32 v96, v96, v116
	v_add_f32_e32 v97, v97, v117
	v_add_f32_e32 v98, v98, v118
	v_add_f32_e32 v99, v99, v119
	v_add_f32_e32 v96, v96, v120
	v_add_f32_e32 v97, v97, v121
	v_add_f32_e32 v98, v98, v122
	v_add_f32_e32 v99, v99, v123
	v_add_f32_e32 v96, v96, v124
	v_add_f32_e32 v97, v97, v125
	v_add_f32_e32 v98, v98, v126
	v_add_f32_e32 v99, v99, v127
	v_lshlrev_b32_e32 v228, 16, v224
	v_and_b32_e32 v229, 0xffff0000, v224
	v_lshlrev_b32_e32 v230, 16, v225
	v_and_b32_e32 v231, 0xffff0000, v225
	v_lshlrev_b32_e32 v232, 16, v226
	v_and_b32_e32 v233, 0xffff0000, v226
	v_lshlrev_b32_e32 v234, 16, v227
	v_and_b32_e32 v235, 0xffff0000, v227
	v_mul_f32_e32 v236, v232, v96
	v_mul_f32_e32 v237, v233, v97
	v_mul_f32_e32 v238, v234, v98
	v_mul_f32_e32 v239, v235, v99
	v_fma_f32 v236, v228, v64, v236
	v_fma_f32 v237, v229, v65, v237
	v_fma_f32 v238, v230, v66, v238
	v_fma_f32 v239, v231, v67, v239
	v_cvt_pk_bf16_f32 v244, v236, v237
	v_cvt_pk_bf16_f32 v245, v238, v239
	global_store_dwordx2 v7, v[244:245], s[12:13]
.Lmini4_done:
.LBB0_1050:
	s_cmp_gt_i32 s19, 5
	s_cselect_b64 s[0:1], -1, 0
	s_and_b64 s[4:5], s[4:5], s[0:1]
	s_andn2_b64 vcc, exec, s[4:5]
	s_cbranch_vccnz .LBB0_1081
	s_waitcnt vmcnt(0)
	s_waitcnt vmcnt(0)
	s_barrier
	s_mov_b32 s3, 0
	s_nop 0
	v_mbcnt_lo_u32_b32 v0, -1, s3
	v_mbcnt_hi_u32_b32 v0, -1, v0
	v_or_b32_e32 v0, s24, v0
	s_nop 0
	v_cmp_eq_u32_e32 vcc, 0, v0
	s_and_saveexec_b64 s[4:5], vcc
	s_cbranch_execz .LBB0_1080
	s_add_i32 s6, 0, 0x23ff0
	v_mov_b32_e32 v0, s6
	s_waitcnt vmcnt(0) expcnt(0) lgkmcnt(0)
	s_getreg_b32 s3, hwreg(HW_REG_XCC_ID, 0, 4)
	ds_read_b32 v1, v0
	s_add_i32 s6, 0, 0x23ff4
	v_mov_b32_e32 v0, s6
	ds_read_b32 v0, v0
	s_and_b32 s3, s3, 15
	s_waitcnt lgkmcnt(1)
	v_cmp_ne_u32_e32 vcc, 0, v1
	s_cbranch_vccnz .LBB0_1058
	s_add_u32 s6, s22, 0x1f32a400
	s_addc_u32 s7, s23, 0
	s_add_u32 s8, s22, 0x1f32a500
	s_addc_u32 s9, s23, 0
	s_add_u32 s10, s22, 0x1f32a600
	s_addc_u32 s11, s23, 0
	s_add_u32 s12, s22, 0x1f32a700
	s_addc_u32 s13, s23, 0
	s_add_u32 s14, s22, 0x1f32a800
	s_addc_u32 s15, s23, 0
	s_add_u32 s16, s22, 0x1f32a900
	s_addc_u32 s17, s23, 0
	s_add_u32 s26, s22, 0x1f32aa00
	s_addc_u32 s27, s23, 0
	s_add_u32 s28, s22, 0x1f32ab00
	s_addc_u32 s29, s23, 0
	s_add_u32 s30, s22, 0x1f32ac00
	s_addc_u32 s31, s23, 0
	s_add_u32 s34, s22, 0x1f32ad00
	s_addc_u32 s35, s23, 0
	s_add_u32 s36, s22, 0x1f32ae00
	s_addc_u32 s37, s23, 0
	s_add_u32 s38, s22, 0x1f32af00
	s_addc_u32 s39, s23, 0
	s_add_u32 s40, s22, 0x1f32b000
	s_addc_u32 s41, s23, 0
	s_add_u32 s42, s22, 0x1f32b100
	s_addc_u32 s43, s23, 0
	s_add_u32 s44, s22, 0x1f32b200
	s_addc_u32 s45, s23, 0
	s_add_u32 s46, s22, 0x1f32b300
	s_addc_u32 s47, s23, 0
	v_mov_b32_e32 v16, 0
	s_branch .LBB0_1055

; #define LAS __attribute__((address_space(3)))
; __device__ __forceinline__ u32x2 f32_to_bf4(f32x4 v) { u32x2 w; w.x = pk2(v[0], v[1]); w.y = pk2(v[2], v[3]); return w; }
; __device__ __forceinline__ f32x4 mini_acc(const bf16_t* A, int lda, const bf16_t* Bt, int ldb, int K, int n0, int wave, int fr, int fq, LAS unsigned char* lds) {
;     asm volatile("" : "+s"(lda), "+s"(ldb));
;     const int lane = fq * 16 + fr, ks = K >> 3;
;     const bf16_t* ap = A + (size_t)(MP + fr) * lda + wave * ks + 8 * fq;
;     const bf16_t* bp = Bt + (size_t)(n0 + fr) * ldb + wave * ks + 8 * fq;
;     f32x4 acc[8];
; #pragma unroll
;     for (int m = 0; m < 8; ++m) acc[m] = (f32x4){0.f, 0.f, 0.f, 0.f};
;     for (int k = 0; k < ks; k += 64) {
;         const bool two = (k + 32 < ks);
;         bf16x8 bq[2], aq[2][8];
;         bq[0] = *(const bf16x8*)(bp + k);
; #pragma unroll
;         for (int m = 0; m < 8; ++m) aq[0][m] = *(const bf16x8*)(ap + (size_t)(16 * m) * lda + k);
;         if (two) { bq[1] = *(const bf16x8*)(bp + k + 32);
; #pragma unroll
;             for (int m = 0; m < 8; ++m) aq[1][m] = *(const bf16x8*)(ap + (size_t)(16 * m) * lda + k + 32); }
; #pragma unroll
;         for (int m = 0; m < 8; ++m) acc[m] = __builtin_amdgcn_mfma_f32_16x16x32_bf16(bq[0], aq[0][m], acc[m], 0, 0, 0);
;         if (two) {
; #pragma unroll
;             for (int m = 0; m < 8; ++m) acc[m] = __builtin_amdgcn_mfma_f32_16x16x32_bf16(bq[1], aq[1][m], acc[m], 0, 0, 0); }
; __global__ void __launch_bounds__(512, 2) mega(Params p) {
;     ...
;         {
;             const int tid = opaque_tid(wave_s), lane = tid & 63, wave = tid >> 6, fr = lane & 15, fq = lane >> 4;
;             for (int nt = bx; nt < 128; nt += G) { const int n0 = nt * 16;
;                 const f32x4 a1 = mini_acc((const bf16_t*)(ws + WS_MERGED), DM, (const bf16_t*)(ws + WS_WO), DM, DM, n0, wave, fr, fq, lds);
;                 const size_t r = MP + 16 * wave + fr; const int c = n0 + 4 * fq;
;                 *(u32x2*)((bf16_t*)(ws + WS_X1) + r * DM + c) = f32_to_bf4(*(const f32x4*)(p.in[1] + (r - MP) * DM + c) + a1); }
.LBB0_1140:
	s_mov_b64 exec, -1
	s_cmpk_gt_u32 s2, 0xff
	s_cbranch_scc1 .Lmini5_done
	v_mbcnt_lo_u32_b32 v0, -1, 0
	v_mbcnt_hi_u32_b32 v0, -1, v0
	v_and_b32_e32 v1, 15, v0
	v_lshrrev_b32_e32 v2, 4, v0
	s_lshr_b32 s84, s24, 6
	s_and_b32 s85, s2, 7
	s_lshr_b32 s86, s2, 4
	s_lshl_b32 s86, s86, 3
	s_or_b32 s85, s85, s86
	s_lshl_b32 s85, s85, 4
	s_bfe_u32 s86, s2, 0x10003
	s_lshl_b32 s86, s86, 6
	s_addk_i32 s86, 0x2000
	v_lshlrev_b32_e32 v20, 4, v0
	s_lshl_b32 s87, s84, 12
	v_add_u32_e32 v20, s87, v20
	v_lshlrev_b32_e32 v21, 4, v0
	s_lshl_b32 s87, s84, 10
	v_add_u32_e32 v21, s87, v21
	s_add_u32 s90, s22, 0xe8aa000
	s_addc_u32 s91, s23, 0
	s_add_u32 s92, s22, 0xc80000
	s_addc_u32 s93, s23, 0
	s_mul_i32 s87, s84, 0x200
	v_lshl_add_u32 v3, v2, 4, s87
	v_add_u32_e32 v4, s86, v1
	s_mov_b32 s88, 0x1000
	v_mul_lo_u32 v5, v4, s88
	v_add_u32_e32 v10, v5, v3
	v_add_u32_e32 v11, 0x10000, v10
	v_add_u32_e32 v12, 0x20000, v10
	v_add_u32_e32 v13, 0x30000, v10
	v_add_u32_e32 v4, s85, v1
	s_mov_b32 s88, 0x1000
	v_mul_lo_u32 v5, v4, s88
	v_add_u32_e32 v14, v5, v3
	v_mov_b32_e32 v32, 0
	v_mov_b32_e32 v33, 0
	v_mov_b32_e32 v34, 0
	v_mov_b32_e32 v35, 0
	v_mov_b32_e32 v36, 0
	v_mov_b32_e32 v37, 0
	v_mov_b32_e32 v38, 0
	v_mov_b32_e32 v39, 0
	v_mov_b32_e32 v40, 0
	v_mov_b32_e32 v41, 0
	v_mov_b32_e32 v42, 0
	v_mov_b32_e32 v43, 0
	v_mov_b32_e32 v44, 0
	v_mov_b32_e32 v45, 0
	v_mov_b32_e32 v46, 0
	v_mov_b32_e32 v47, 0
	s_cmp_gt_u32 s84, 3
	s_cbranch_scc1 .Lmini5_noepi
	s_lshl_b32 s87, s84, 4
	s_add_i32 s87, s87, s86
	v_add_u32_e32 v4, s87, v1
	v_lshl_add_u32 v5, v2, 2, s85
	v_lshlrev_b32_e32 v7, 12, v4
	v_lshl_add_u32 v7, v5, 1, v7
	s_add_u32 s12, s22, 0x17d2a000
	s_addc_u32 s13, s23, 0
	v_add_u32_e32 v6, 0xffffe000, v4
	v_lshlrev_b32_e32 v6, 13, v6
	v_lshl_add_u32 v6, v5, 2, v6
	global_load_dwordx4 v[224:227], v6, s[54:55]
.Lmini5_noepi:
	global_load_dwordx4 v[64:67], v14, s[92:93]
	global_load_dwordx4 v[68:71], v10, s[90:91]
	global_load_dwordx4 v[72:75], v11, s[90:91]
	global_load_dwordx4 v[76:79], v12, s[90:91]
	global_load_dwordx4 v[80:83], v13, s[90:91]
	global_load_dwordx4 v[84:87], v14, s[92:93] offset:64
	global_load_dwordx4 v[88:91], v10, s[90:91] offset:64
	global_load_dwordx4 v[92:95], v11, s[90:91] offset:64
	global_load_dwordx4 v[96:99], v12, s[90:91] offset:64
	global_load_dwordx4 v[100:103], v13, s[90:91] offset:64
	global_load_dwordx4 v[104:107], v14, s[92:93] offset:128
	global_load_dwordx4 v[108:111], v10, s[90:91] offset:128
	global_load_dwordx4 v[112:115], v11, s[90:91] offset:128
	global_load_dwordx4 v[116:119], v12, s[90:91] offset:128
	global_load_dwordx4 v[120:123], v13, s[90:91] offset:128
	global_load_dwordx4 v[124:127], v14, s[92:93] offset:192
	global_load_dwordx4 v[128:131], v10, s[90:91] offset:192
	global_load_dwordx4 v[132:135], v11, s[90:91] offset:192
	global_load_dwordx4 v[136:139], v12, s[90:91] offset:192
	global_load_dwordx4 v[140:143], v13, s[90:91] offset:192
	global_load_dwordx4 v[144:147], v14, s[92:93] offset:256
	global_load_dwordx4 v[148:151], v10, s[90:91] offset:256
	global_load_dwordx4 v[152:155], v11, s[90:91] offset:256
	global_load_dwordx4 v[156:159], v12, s[90:91] offset:256
	global_load_dwordx4 v[160:163], v13, s[90:91] offset:256
	global_load_dwordx4 v[164:167], v14, s[92:93] offset:320
	global_load_dwordx4 v[168:171], v10, s[90:91] offset:320
	global_load_dwordx4 v[172:175], v11, s[90:91] offset:320
	global_load_dwordx4 v[176:179], v12, s[90:91] offset:320
	global_load_dwordx4 v[180:183], v13, s[90:91] offset:320
	global_load_dwordx4 v[184:187], v14, s[92:93] offset:384
	global_load_dwordx4 v[188:191], v10, s[90:91] offset:384
	global_load_dwordx4 v[192:195], v11, s[90:91] offset:384
	global_load_dwordx4 v[196:199], v12, s[90:91] offset:384
	global_load_dwordx4 v[200:203], v13, s[90:91] offset:384
	global_load_dwordx4 v[204:207], v14, s[92:93] offset:448
	global_load_dwordx4 v[208:211], v10, s[90:91] offset:448
	global_load_dwordx4 v[212:215], v11, s[90:91] offset:448
	global_load_dwordx4 v[216:219], v12, s[90:91] offset:448
	global_load_dwordx4 v[220:223], v13, s[90:91] offset:448
	s_waitcnt vmcnt(35)
	v_mfma_f32_16x16x32_bf16 v[32:35], v[64:67], v[68:71], v[32:35]
	v_mfma_f32_16x16x32_bf16 v[36:39], v[64:67], v[72:75], v[36:39]
	v_mfma_f32_16x16x32_bf16 v[40:43], v[64:67], v[76:79], v[40:43]
	v_mfma_f32_16x16x32_bf16 v[44:47], v[64:67], v[80:83], v[44:47]
	s_waitcnt vmcnt(30)
	v_mfma_f32_16x16x32_bf16 v[32:35], v[84:87], v[88:91], v[32:35]
	v_mfma_f32_16x16x32_bf16 v[36:39], v[84:87], v[92:95], v[36:39]
	v_mfma_f32_16x16x32_bf16 v[40:43], v[84:87], v[96:99], v[40:43]
	v_mfma_f32_16x16x32_bf16 v[44:47], v[84:87], v[100:103], v[44:47]
	s_waitcnt vmcnt(25)
	v_mfma_f32_16x16x32_bf16 v[32:35], v[104:107], v[108:111], v[32:35]
	v_mfma_f32_16x16x32_bf16 v[36:39], v[104:107], v[112:115], v[36:39]
	v_mfma_f32_16x16x32_bf16 v[40:43], v[104:107], v[116:119], v[40:43]
	v_mfma_f32_16x16x32_bf16 v[44:47], v[104:107], v[120:123], v[44:47]
	s_waitcnt vmcnt(20)
	v_mfma_f32_16x16x32_bf16 v[32:35], v[124:127], v[128:131], v[32:35]
	v_mfma_f32_16x16x32_bf16 v[36:39], v[124:127], v[132:135], v[36:39]
	v_mfma_f32_16x16x32_bf16 v[40:43], v[124:127], v[136:139], v[40:43]
	v_mfma_f32_16x16x32_bf16 v[44:47], v[124:127], v[140:143], v[44:47]
	s_waitcnt vmcnt(15)
	v_mfma_f32_16x16x32_bf16 v[32:35], v[144:147], v[148:151], v[32:35]
	v_mfma_f32_16x16x32_bf16 v[36:39], v[144:147], v[152:155], v[36:39]
	v_mfma_f32_16x16x32_bf16 v[40:43], v[144:147], v[156:159], v[40:43]
	v_mfma_f32_16x16x32_bf16 v[44:47], v[144:147], v[160:163], v[44:47]
	s_waitcnt vmcnt(10)
	v_mfma_f32_16x16x32_bf16 v[32:35], v[164:167], v[168:171], v[32:35]
	v_mfma_f32_16x16x32_bf16 v[36:39], v[164:167], v[172:175], v[36:39]
	v_mfma_f32_16x16x32_bf16 v[40:43], v[164:167], v[176:179], v[40:43]
	v_mfma_f32_16x16x32_bf16 v[44:47], v[164:167], v[180:183], v[44:47]
	s_waitcnt vmcnt(5)
	v_mfma_f32_16x16x32_bf16 v[32:35], v[184:187], v[188:191], v[32:35]
	v_mfma_f32_16x16x32_bf16 v[36:39], v[184:187], v[192:195], v[36:39]
	v_mfma_f32_16x16x32_bf16 v[40:43], v[184:187], v[196:199], v[40:43]
	v_mfma_f32_16x16x32_bf16 v[44:47], v[184:187], v[200:203], v[44:47]
	s_waitcnt vmcnt(0)
	v_mfma_f32_16x16x32_bf16 v[32:35], v[204:207], v[208:211], v[32:35]
	v_mfma_f32_16x16x32_bf16 v[36:39], v[204:207], v[212:215], v[36:39]
	v_mfma_f32_16x16x32_bf16 v[40:43], v[204:207], v[216:219], v[40:43]
	v_mfma_f32_16x16x32_bf16 v[44:47], v[204:207], v[220:223], v[44:47]
	s_nop 7
	s_nop 3
	ds_write_b128 v20, v[32:35]
	ds_write_b128 v20, v[36:39] offset:1024
	ds_write_b128 v20, v[40:43] offset:2048
	ds_write_b128 v20, v[44:47] offset:3072
	s_waitcnt lgkmcnt(0)
	s_barrier
; __device__ __forceinline__ u32x2 f32_to_bf4(f32x4 v) { u32x2 w; w.x = pk2(v[0], v[1]); w.y = pk2(v[2], v[3]); return w; }
; __device__ __forceinline__ f32x4 mini_acc(const bf16_t* A, int lda, const bf16_t* Bt, int ldb, int K, int n0, int wave, int fr, int fq, LAS unsigned char* lds) {
;     ...
;     f32x4 r = (f32x4){0.f, 0.f, 0.f, 0.f};
; #pragma unroll
;     for (int w2 = 0; w2 < 8; ++w2) r += RED[(w2 * 8 + wave) * 64 + lane];
; __global__ void __launch_bounds__(512, 2) mega(Params p) {
;     ...
;                 const size_t r = MP + 16 * wave + fr; const int c = n0 + 4 * fq;
;                 *(u32x2*)((bf16_t*)(ws + WS_X1) + r * DM + c) = f32_to_bf4(*(const f32x4*)(p.in[1] + (r - MP) * DM + c) + a1); }
	s_cmp_gt_u32 s84, 3
	s_cbranch_scc1 .Lmini5_done
	ds_read_b128 v[64:67], v21
	ds_read_b128 v[68:71], v21 offset:4096
	ds_read_b128 v[72:75], v21 offset:8192
	ds_read_b128 v[76:79], v21 offset:12288
	ds_read_b128 v[80:83], v21 offset:16384
	ds_read_b128 v[84:87], v21 offset:20480
	ds_read_b128 v[88:91], v21 offset:24576
	ds_read_b128 v[92:95], v21 offset:28672
	s_waitcnt vmcnt(0) lgkmcnt(0)
	v_add_f32_e32 v64, v64, v68
	v_add_f32_e32 v65, v65, v69
	v_add_f32_e32 v66, v66, v70
	v_add_f32_e32 v67, v67, v71
	v_add_f32_e32 v64, v64, v72
	v_add_f32_e32 v65, v65, v73
	v_add_f32_e32 v66, v66, v74
	v_add_f32_e32 v67, v67, v75
	v_add_f32_e32 v64, v64, v76
	v_add_f32_e32 v65, v65, v77
	v_add_f32_e32 v66, v66, v78
	v_add_f32_e32 v67, v67, v79
	v_add_f32_e32 v64, v64, v80
	v_add_f32_e32 v65, v65, v81
	v_add_f32_e32 v66, v66, v82
	v_add_f32_e32 v67, v67, v83
	v_add_f32_e32 v64, v64, v84
	v_add_f32_e32 v65, v65, v85
	v_add_f32_e32 v66, v66, v86
	v_add_f32_e32 v67, v67, v87
	v_add_f32_e32 v64, v64, v88
	v_add_f32_e32 v65, v65, v89
	v_add_f32_e32 v66, v66, v90
	v_add_f32_e32 v67, v67, v91
	v_add_f32_e32 v64, v64, v92
	v_add_f32_e32 v65, v65, v93
	v_add_f32_e32 v66, v66, v94
	v_add_f32_e32 v67, v67, v95
	v_add_f32_e32 v236, v224, v64
	v_add_f32_e32 v237, v225, v65
	v_add_f32_e32 v238, v226, v66
	v_add_f32_e32 v239, v227, v67
	v_cvt_pk_bf16_f32 v244, v236, v237
	v_cvt_pk_bf16_f32 v245, v238, v239
	global_store_dwordx2 v7, v[244:245], s[12:13]
.Lmini5_done:
.LBB0_1143:
	s_cmp_gt_i32 s19, 6
	s_cselect_b64 s[0:1], -1, 0
	s_and_b64 s[4:5], s[4:5], s[0:1]
	s_andn2_b64 vcc, exec, s[4:5]
	s_cbranch_vccnz .LBB0_1174
	s_waitcnt vmcnt(0)
	s_waitcnt vmcnt(0)
	s_barrier
	s_mov_b32 s3, 0
	s_nop 0
	v_mbcnt_lo_u32_b32 v0, -1, s3
	v_mbcnt_hi_u32_b32 v0, -1, v0
	v_or_b32_e32 v0, s24, v0
	s_nop 0
	v_cmp_eq_u32_e32 vcc, 0, v0
	s_and_saveexec_b64 s[4:5], vcc
	s_cbranch_execz .LBB0_1173
	s_add_i32 s6, 0, 0x23ff0
	v_mov_b32_e32 v0, s6
	s_waitcnt vmcnt(0) expcnt(0) lgkmcnt(0)
	s_getreg_b32 s3, hwreg(HW_REG_XCC_ID, 0, 4)
	ds_read_b32 v1, v0
	s_add_i32 s6, 0, 0x23ff4
	v_mov_b32_e32 v0, s6
	ds_read_b32 v0, v0
	s_and_b32 s3, s3, 15
	s_waitcnt lgkmcnt(1)
	v_cmp_ne_u32_e32 vcc, 0, v1
	s_cbranch_vccnz .LBB0_1151
	s_add_u32 s6, s22, 0x1f32a400
	s_addc_u32 s7, s23, 0
	s_add_u32 s8, s22, 0x1f32a500
	s_addc_u32 s9, s23, 0
	s_add_u32 s10, s22, 0x1f32a600
	s_addc_u32 s11, s23, 0
	s_add_u32 s12, s22, 0x1f32a700
	s_addc_u32 s13, s23, 0
	s_add_u32 s14, s22, 0x1f32a800
	s_addc_u32 s15, s23, 0
	s_add_u32 s16, s22, 0x1f32a900
	s_addc_u32 s17, s23, 0
	s_add_u32 s26, s22, 0x1f32aa00
	s_addc_u32 s27, s23, 0
	s_add_u32 s28, s22, 0x1f32ab00
	s_addc_u32 s29, s23, 0
	s_add_u32 s30, s22, 0x1f32ac00
	s_addc_u32 s31, s23, 0
	s_add_u32 s34, s22, 0x1f32ad00
	s_addc_u32 s35, s23, 0
	s_add_u32 s36, s22, 0x1f32ae00
	s_addc_u32 s37, s23, 0
	s_add_u32 s38, s22, 0x1f32af00
	s_addc_u32 s39, s23, 0
	s_add_u32 s40, s22, 0x1f32b000
	s_addc_u32 s41, s23, 0
	s_add_u32 s42, s22, 0x1f32b100
	s_addc_u32 s43, s23, 0
	s_add_u32 s44, s22, 0x1f32b200
	s_addc_u32 s45, s23, 0
	s_add_u32 s46, s22, 0x1f32b300
	s_addc_u32 s47, s23, 0
	v_mov_b32_e32 v16, 0
	s_branch .LBB0_1148

; #define LAS __attribute__((address_space(3)))
; __device__ __forceinline__ f32x4 mini_acc(const bf16_t* A, int lda, const bf16_t* Bt, int ldb, int K, int n0, int wave, int fr, int fq, LAS unsigned char* lds) {
;     asm volatile("" : "+s"(lda), "+s"(ldb));
;     const int lane = fq * 16 + fr, ks = K >> 3;
;     const bf16_t* ap = A + (size_t)(MP + fr) * lda + wave * ks + 8 * fq;
;     const bf16_t* bp = Bt + (size_t)(n0 + fr) * ldb + wave * ks + 8 * fq;
;     f32x4 acc[8];
; #pragma unroll
;     for (int m = 0; m < 8; ++m) acc[m] = (f32x4){0.f, 0.f, 0.f, 0.f};
;     for (int k = 0; k < ks; k += 64) {
;         const bool two = (k + 32 < ks);
;         bf16x8 bq[2], aq[2][8];
;         bq[0] = *(const bf16x8*)(bp + k);
; #pragma unroll
;         for (int m = 0; m < 8; ++m) aq[0][m] = *(const bf16x8*)(ap + (size_t)(16 * m) * lda + k);
;         if (two) { bq[1] = *(const bf16x8*)(bp + k + 32);
; #pragma unroll
;             for (int m = 0; m < 8; ++m) aq[1][m] = *(const bf16x8*)(ap + (size_t)(16 * m) * lda + k + 32); }
; #pragma unroll
;         for (int m = 0; m < 8; ++m) acc[m] = __builtin_amdgcn_mfma_f32_16x16x32_bf16(bq[0], aq[0][m], acc[m], 0, 0, 0);
;         if (two) {
; #pragma unroll
;             for (int m = 0; m < 8; ++m) acc[m] = __builtin_amdgcn_mfma_f32_16x16x32_bf16(bq[1], aq[1][m], acc[m], 0, 0, 0); }
; __global__ void __launch_bounds__(512, 2) mega(Params p) {
;     ...
;         {
;             const int tid = opaque_tid(wave_s), lane = tid & 63, wave = tid >> 6, fr = lane & 15, fq = lane >> 4;
;             for (int nt = bx; nt < 128; nt += G) { const int n0 = nt * 16;
;                 const f32x4 a1 = mini_acc((const bf16_t*)(ws + WS_ACT), DFF, (const bf16_t*)(ws + WS_WDOWN), DFF, DFF, n0, wave, fr, fq, lds);
.LBB0_1295:
	s_mov_b64 exec, -1
	s_cmpk_gt_u32 s2, 0xff
	s_cbranch_scc1 .Lmini8_done
	v_mbcnt_lo_u32_b32 v0, -1, 0
	v_mbcnt_hi_u32_b32 v0, -1, v0
	v_and_b32_e32 v1, 15, v0
	v_lshrrev_b32_e32 v2, 4, v0
	s_lshr_b32 s84, s24, 6
	s_and_b32 s85, s2, 7
	s_lshr_b32 s86, s2, 4
	s_lshl_b32 s86, s86, 3
	s_or_b32 s85, s85, s86
	s_lshl_b32 s85, s85, 4
	s_bfe_u32 s86, s2, 0x10003
	s_lshl_b32 s86, s86, 6
	s_addk_i32 s86, 0x2000
	v_lshlrev_b32_e32 v20, 4, v0
	s_lshl_b32 s87, s84, 12
	v_add_u32_e32 v20, s87, v20
	v_lshlrev_b32_e32 v21, 4, v0
	s_lshl_b32 s87, s84, 10
	v_add_u32_e32 v21, s87, v21
	s_add_u32 s90, s22, 0xa6aa000
	s_addc_u32 s91, s23, 0
	s_add_u32 s92, s22, 0x4080000
	s_addc_u32 s93, s23, 0
	s_mul_i32 s87, s84, 0x580
	v_lshl_add_u32 v3, v2, 4, s87
	v_add_u32_e32 v4, s86, v1
	s_mov_b32 s88, 0x2c00
	v_mul_lo_u32 v5, v4, s88
	v_add_u32_e32 v10, v5, v3
	v_add_u32_e32 v11, 0x2c000, v10
	v_add_u32_e32 v12, 0x58000, v10
	v_add_u32_e32 v13, 0x84000, v10
	v_add_u32_e32 v4, s85, v1
	s_mov_b32 s88, 0x2c00
	v_mul_lo_u32 v5, v4, s88
	v_add_u32_e32 v14, v5, v3
	v_mov_b32_e32 v32, 0
	v_mov_b32_e32 v33, 0
	v_mov_b32_e32 v34, 0
	v_mov_b32_e32 v35, 0
	v_mov_b32_e32 v36, 0
	v_mov_b32_e32 v37, 0
	v_mov_b32_e32 v38, 0
	v_mov_b32_e32 v39, 0
	v_mov_b32_e32 v40, 0
	v_mov_b32_e32 v41, 0
	v_mov_b32_e32 v42, 0
	v_mov_b32_e32 v43, 0
	v_mov_b32_e32 v44, 0
	v_mov_b32_e32 v45, 0
	v_mov_b32_e32 v46, 0
	v_mov_b32_e32 v47, 0
	s_cmp_gt_u32 s84, 3
	s_cbranch_scc1 .Lmini8_noepi
	s_lshl_b32 s87, s84, 4
	s_add_i32 s87, s87, s86
	v_add_u32_e32 v4, s87, v1
	v_lshl_add_u32 v5, v2, 2, s85
	v_lshlrev_b32_e32 v7, 12, v4
	v_lshl_add_u32 v7, v5, 1, v7
	s_add_u32 s8, s22, 0x17d2a000
	s_addc_u32 s9, s23, 0
	s_add_u32 s12, s22, 0x85aa000
	s_addc_u32 s13, s23, 0
	global_load_dwordx2 v[224:225], v7, s[8:9]
.Lmini8_noepi:
	global_load_dwordx4 v[64:67], v14, s[92:93]
	global_load_dwordx4 v[68:71], v10, s[90:91]
	global_load_dwordx4 v[72:75], v11, s[90:91]
	global_load_dwordx4 v[76:79], v12, s[90:91]
	global_load_dwordx4 v[80:83], v13, s[90:91]
	global_load_dwordx4 v[84:87], v14, s[92:93] offset:64
	global_load_dwordx4 v[88:91], v10, s[90:91] offset:64
	global_load_dwordx4 v[92:95], v11, s[90:91] offset:64
	global_load_dwordx4 v[96:99], v12, s[90:91] offset:64
	global_load_dwordx4 v[100:103], v13, s[90:91] offset:64
	global_load_dwordx4 v[104:107], v14, s[92:93] offset:128
	global_load_dwordx4 v[108:111], v10, s[90:91] offset:128
	global_load_dwordx4 v[112:115], v11, s[90:91] offset:128
	global_load_dwordx4 v[116:119], v12, s[90:91] offset:128
	global_load_dwordx4 v[120:123], v13, s[90:91] offset:128
	global_load_dwordx4 v[124:127], v14, s[92:93] offset:192
	global_load_dwordx4 v[128:131], v10, s[90:91] offset:192
	global_load_dwordx4 v[132:135], v11, s[90:91] offset:192
	global_load_dwordx4 v[136:139], v12, s[90:91] offset:192
	global_load_dwordx4 v[140:143], v13, s[90:91] offset:192
	global_load_dwordx4 v[144:147], v14, s[92:93] offset:256
	global_load_dwordx4 v[148:151], v10, s[90:91] offset:256
	global_load_dwordx4 v[152:155], v11, s[90:91] offset:256
	global_load_dwordx4 v[156:159], v12, s[90:91] offset:256
	global_load_dwordx4 v[160:163], v13, s[90:91] offset:256
	global_load_dwordx4 v[164:167], v14, s[92:93] offset:320
	global_load_dwordx4 v[168:171], v10, s[90:91] offset:320
	global_load_dwordx4 v[172:175], v11, s[90:91] offset:320
	global_load_dwordx4 v[176:179], v12, s[90:91] offset:320
	global_load_dwordx4 v[180:183], v13, s[90:91] offset:320
	global_load_dwordx4 v[184:187], v14, s[92:93] offset:384
	global_load_dwordx4 v[188:191], v10, s[90:91] offset:384
	global_load_dwordx4 v[192:195], v11, s[90:91] offset:384
	global_load_dwordx4 v[196:199], v12, s[90:91] offset:384
	global_load_dwordx4 v[200:203], v13, s[90:91] offset:384
	global_load_dwordx4 v[204:207], v14, s[92:93] offset:448
	global_load_dwordx4 v[208:211], v10, s[90:91] offset:448
	global_load_dwordx4 v[212:215], v11, s[90:91] offset:448
	global_load_dwordx4 v[216:219], v12, s[90:91] offset:448
	global_load_dwordx4 v[220:223], v13, s[90:91] offset:448
	s_waitcnt vmcnt(35)
	v_mfma_f32_16x16x32_bf16 v[32:35], v[64:67], v[68:71], v[32:35]
	v_mfma_f32_16x16x32_bf16 v[36:39], v[64:67], v[72:75], v[36:39]
	v_mfma_f32_16x16x32_bf16 v[40:43], v[64:67], v[76:79], v[40:43]
	v_mfma_f32_16x16x32_bf16 v[44:47], v[64:67], v[80:83], v[44:47]
	global_load_dwordx4 v[64:67], v14, s[92:93] offset:512
	global_load_dwordx4 v[68:71], v10, s[90:91] offset:512
	global_load_dwordx4 v[72:75], v11, s[90:91] offset:512
	global_load_dwordx4 v[76:79], v12, s[90:91] offset:512
	global_load_dwordx4 v[80:83], v13, s[90:91] offset:512
	s_waitcnt vmcnt(35)
	v_mfma_f32_16x16x32_bf16 v[32:35], v[84:87], v[88:91], v[32:35]
	v_mfma_f32_16x16x32_bf16 v[36:39], v[84:87], v[92:95], v[36:39]
	v_mfma_f32_16x16x32_bf16 v[40:43], v[84:87], v[96:99], v[40:43]
	v_mfma_f32_16x16x32_bf16 v[44:47], v[84:87], v[100:103], v[44:47]
	global_load_dwordx4 v[84:87], v14, s[92:93] offset:576
	global_load_dwordx4 v[88:91], v10, s[90:91] offset:576
	global_load_dwordx4 v[92:95], v11, s[90:91] offset:576
	global_load_dwordx4 v[96:99], v12, s[90:91] offset:576
	global_load_dwordx4 v[100:103], v13, s[90:91] offset:576
	s_waitcnt vmcnt(35)
	v_mfma_f32_16x16x32_bf16 v[32:35], v[104:107], v[108:111], v[32:35]
	v_mfma_f32_16x16x32_bf16 v[36:39], v[104:107], v[112:115], v[36:39]
	v_mfma_f32_16x16x32_bf16 v[40:43], v[104:107], v[116:119], v[40:43]
	v_mfma_f32_16x16x32_bf16 v[44:47], v[104:107], v[120:123], v[44:47]
	global_load_dwordx4 v[104:107], v14, s[92:93] offset:640
	global_load_dwordx4 v[108:111], v10, s[90:91] offset:640
	global_load_dwordx4 v[112:115], v11, s[90:91] offset:640
	global_load_dwordx4 v[116:119], v12, s[90:91] offset:640
	global_load_dwordx4 v[120:123], v13, s[90:91] offset:640
	s_waitcnt vmcnt(35)
; __device__ __forceinline__ f32x4 mini_acc(const bf16_t* A, int lda, const bf16_t* Bt, int ldb, int K, int n0, int wave, int fr, int fq, LAS unsigned char* lds) {
;     ...
;     for (int k = 0; k < ks; k += 64) {
;         const bool two = (k + 32 < ks);
;         bf16x8 bq[2], aq[2][8];
;         bq[0] = *(const bf16x8*)(bp + k);
; #pragma unroll
;         for (int m = 0; m < 8; ++m) aq[0][m] = *(const bf16x8*)(ap + (size_t)(16 * m) * lda + k);
;         if (two) { bq[1] = *(const bf16x8*)(bp + k + 32);
; #pragma unroll
;             for (int m = 0; m < 8; ++m) aq[1][m] = *(const bf16x8*)(ap + (size_t)(16 * m) * lda + k + 32); }
; #pragma unroll
;         for (int m = 0; m < 8; ++m) acc[m] = __builtin_amdgcn_mfma_f32_16x16x32_bf16(bq[0], aq[0][m], acc[m], 0, 0, 0);
;         if (two) {
; #pragma unroll
;             for (int m = 0; m < 8; ++m) acc[m] = __builtin_amdgcn_mfma_f32_16x16x32_bf16(bq[1], aq[1][m], acc[m], 0, 0, 0); }
;     }
	v_mfma_f32_16x16x32_bf16 v[32:35], v[124:127], v[128:131], v[32:35]
	v_mfma_f32_16x16x32_bf16 v[36:39], v[124:127], v[132:135], v[36:39]
	v_mfma_f32_16x16x32_bf16 v[40:43], v[124:127], v[136:139], v[40:43]
	v_mfma_f32_16x16x32_bf16 v[44:47], v[124:127], v[140:143], v[44:47]
	global_load_dwordx4 v[124:127], v14, s[92:93] offset:704
	global_load_dwordx4 v[128:131], v10, s[90:91] offset:704
	global_load_dwordx4 v[132:135], v11, s[90:91] offset:704
	global_load_dwordx4 v[136:139], v12, s[90:91] offset:704
	global_load_dwordx4 v[140:143], v13, s[90:91] offset:704
	s_waitcnt vmcnt(35)
	v_mfma_f32_16x16x32_bf16 v[32:35], v[144:147], v[148:151], v[32:35]
	v_mfma_f32_16x16x32_bf16 v[36:39], v[144:147], v[152:155], v[36:39]
	v_mfma_f32_16x16x32_bf16 v[40:43], v[144:147], v[156:159], v[40:43]
	v_mfma_f32_16x16x32_bf16 v[44:47], v[144:147], v[160:163], v[44:47]
	global_load_dwordx4 v[144:147], v14, s[92:93] offset:768
	global_load_dwordx4 v[148:151], v10, s[90:91] offset:768
	global_load_dwordx4 v[152:155], v11, s[90:91] offset:768
	global_load_dwordx4 v[156:159], v12, s[90:91] offset:768
	global_load_dwordx4 v[160:163], v13, s[90:91] offset:768
	s_waitcnt vmcnt(35)
	v_mfma_f32_16x16x32_bf16 v[32:35], v[164:167], v[168:171], v[32:35]
	v_mfma_f32_16x16x32_bf16 v[36:39], v[164:167], v[172:175], v[36:39]
	v_mfma_f32_16x16x32_bf16 v[40:43], v[164:167], v[176:179], v[40:43]
	v_mfma_f32_16x16x32_bf16 v[44:47], v[164:167], v[180:183], v[44:47]
	global_load_dwordx4 v[164:167], v14, s[92:93] offset:832
	global_load_dwordx4 v[168:171], v10, s[90:91] offset:832
	global_load_dwordx4 v[172:175], v11, s[90:91] offset:832
	global_load_dwordx4 v[176:179], v12, s[90:91] offset:832
	global_load_dwordx4 v[180:183], v13, s[90:91] offset:832
	s_waitcnt vmcnt(35)
	v_mfma_f32_16x16x32_bf16 v[32:35], v[184:187], v[188:191], v[32:35]
	v_mfma_f32_16x16x32_bf16 v[36:39], v[184:187], v[192:195], v[36:39]
	v_mfma_f32_16x16x32_bf16 v[40:43], v[184:187], v[196:199], v[40:43]
	v_mfma_f32_16x16x32_bf16 v[44:47], v[184:187], v[200:203], v[44:47]
	global_load_dwordx4 v[184:187], v14, s[92:93] offset:896
	global_load_dwordx4 v[188:191], v10, s[90:91] offset:896
	global_load_dwordx4 v[192:195], v11, s[90:91] offset:896
	global_load_dwordx4 v[196:199], v12, s[90:91] offset:896
	global_load_dwordx4 v[200:203], v13, s[90:91] offset:896
	s_waitcnt vmcnt(35)
	v_mfma_f32_16x16x32_bf16 v[32:35], v[204:207], v[208:211], v[32:35]
	v_mfma_f32_16x16x32_bf16 v[36:39], v[204:207], v[212:215], v[36:39]
	v_mfma_f32_16x16x32_bf16 v[40:43], v[204:207], v[216:219], v[40:43]
	v_mfma_f32_16x16x32_bf16 v[44:47], v[204:207], v[220:223], v[44:47]
	global_load_dwordx4 v[204:207], v14, s[92:93] offset:960
	global_load_dwordx4 v[208:211], v10, s[90:91] offset:960
	global_load_dwordx4 v[212:215], v11, s[90:91] offset:960
	global_load_dwordx4 v[216:219], v12, s[90:91] offset:960
	global_load_dwordx4 v[220:223], v13, s[90:91] offset:960
	s_waitcnt vmcnt(35)
	v_mfma_f32_16x16x32_bf16 v[32:35], v[64:67], v[68:71], v[32:35]
	v_mfma_f32_16x16x32_bf16 v[36:39], v[64:67], v[72:75], v[36:39]
	v_mfma_f32_16x16x32_bf16 v[40:43], v[64:67], v[76:79], v[40:43]
	v_mfma_f32_16x16x32_bf16 v[44:47], v[64:67], v[80:83], v[44:47]
	global_load_dwordx4 v[64:67], v14, s[92:93] offset:1024
	global_load_dwordx4 v[68:71], v10, s[90:91] offset:1024
	global_load_dwordx4 v[72:75], v11, s[90:91] offset:1024
	global_load_dwordx4 v[76:79], v12, s[90:91] offset:1024
	global_load_dwordx4 v[80:83], v13, s[90:91] offset:1024
	s_waitcnt vmcnt(35)
	v_mfma_f32_16x16x32_bf16 v[32:35], v[84:87], v[88:91], v[32:35]
	v_mfma_f32_16x16x32_bf16 v[36:39], v[84:87], v[92:95], v[36:39]
	v_mfma_f32_16x16x32_bf16 v[40:43], v[84:87], v[96:99], v[40:43]
	v_mfma_f32_16x16x32_bf16 v[44:47], v[84:87], v[100:103], v[44:47]
	global_load_dwordx4 v[84:87], v14, s[92:93] offset:1088
	global_load_dwordx4 v[88:91], v10, s[90:91] offset:1088
	global_load_dwordx4 v[92:95], v11, s[90:91] offset:1088
	global_load_dwordx4 v[96:99], v12, s[90:91] offset:1088
	global_load_dwordx4 v[100:103], v13, s[90:91] offset:1088
	s_waitcnt vmcnt(35)
	v_mfma_f32_16x16x32_bf16 v[32:35], v[104:107], v[108:111], v[32:35]
	v_mfma_f32_16x16x32_bf16 v[36:39], v[104:107], v[112:115], v[36:39]
	v_mfma_f32_16x16x32_bf16 v[40:43], v[104:107], v[116:119], v[40:43]
	v_mfma_f32_16x16x32_bf16 v[44:47], v[104:107], v[120:123], v[44:47]
	global_load_dwordx4 v[104:107], v14, s[92:93] offset:1152
	global_load_dwordx4 v[108:111], v10, s[90:91] offset:1152
	global_load_dwordx4 v[112:115], v11, s[90:91] offset:1152
	global_load_dwordx4 v[116:119], v12, s[90:91] offset:1152
	global_load_dwordx4 v[120:123], v13, s[90:91] offset:1152
	s_waitcnt vmcnt(35)
	v_mfma_f32_16x16x32_bf16 v[32:35], v[124:127], v[128:131], v[32:35]
	v_mfma_f32_16x16x32_bf16 v[36:39], v[124:127], v[132:135], v[36:39]
	v_mfma_f32_16x16x32_bf16 v[40:43], v[124:127], v[136:139], v[40:43]
	v_mfma_f32_16x16x32_bf16 v[44:47], v[124:127], v[140:143], v[44:47]
	global_load_dwordx4 v[124:127], v14, s[92:93] offset:1216
	global_load_dwordx4 v[128:131], v10, s[90:91] offset:1216
	global_load_dwordx4 v[132:135], v11, s[90:91] offset:1216
	global_load_dwordx4 v[136:139], v12, s[90:91] offset:1216
	global_load_dwordx4 v[140:143], v13, s[90:91] offset:1216
	s_waitcnt vmcnt(35)
	v_mfma_f32_16x16x32_bf16 v[32:35], v[144:147], v[148:151], v[32:35]
	v_mfma_f32_16x16x32_bf16 v[36:39], v[144:147], v[152:155], v[36:39]
	v_mfma_f32_16x16x32_bf16 v[40:43], v[144:147], v[156:159], v[40:43]
	v_mfma_f32_16x16x32_bf16 v[44:47], v[144:147], v[160:163], v[44:47]
	global_load_dwordx4 v[144:147], v14, s[92:93] offset:1280
	global_load_dwordx4 v[148:151], v10, s[90:91] offset:1280
	global_load_dwordx4 v[152:155], v11, s[90:91] offset:1280
	global_load_dwordx4 v[156:159], v12, s[90:91] offset:1280
	global_load_dwordx4 v[160:163], v13, s[90:91] offset:1280
	s_waitcnt vmcnt(35)
; #define LAS __attribute__((address_space(3)))
; #define BAR_LDS() do { asm volatile("s_waitcnt lgkmcnt(0)" ::: "memory"); __builtin_amdgcn_s_barrier(); asm volatile("" ::: "memory"); } while (0)
; __device__ __forceinline__ f32x4 bf4_to_f32(u32x2 w) { return (f32x4){bflo(w.x), bfhi(w.x), bflo(w.y), bfhi(w.y)}; }
; __device__ __forceinline__ u32x2 f32_to_bf4(f32x4 v) { u32x2 w; w.x = pk2(v[0], v[1]); w.y = pk2(v[2], v[3]); return w; }
; __device__ __forceinline__ f32x4 mini_acc(const bf16_t* A, int lda, const bf16_t* Bt, int ldb, int K, int n0, int wave, int fr, int fq, LAS unsigned char* lds) {
;     ...
;     for (int k = 0; k < ks; k += 64) {
;         const bool two = (k + 32 < ks);
;         bf16x8 bq[2], aq[2][8];
;         bq[0] = *(const bf16x8*)(bp + k);
; #pragma unroll
;         for (int m = 0; m < 8; ++m) aq[0][m] = *(const bf16x8*)(ap + (size_t)(16 * m) * lda + k);
;         if (two) { bq[1] = *(const bf16x8*)(bp + k + 32);
; #pragma unroll
;             for (int m = 0; m < 8; ++m) aq[1][m] = *(const bf16x8*)(ap + (size_t)(16 * m) * lda + k + 32); }
; #pragma unroll
;         for (int m = 0; m < 8; ++m) acc[m] = __builtin_amdgcn_mfma_f32_16x16x32_bf16(bq[0], aq[0][m], acc[m], 0, 0, 0);
;         if (two) {
; #pragma unroll
;             for (int m = 0; m < 8; ++m) acc[m] = __builtin_amdgcn_mfma_f32_16x16x32_bf16(bq[1], aq[1][m], acc[m], 0, 0, 0); }
;     }
;     LAS f32x4* RED = (LAS f32x4*)lds;
; #pragma unroll
;     for (int m = 0; m < 8; ++m) RED[(wave * 8 + m) * 64 + lane] = acc[m];
;     BAR_LDS();
;     f32x4 r = (f32x4){0.f, 0.f, 0.f, 0.f};
; #pragma unroll
;     for (int w2 = 0; w2 < 8; ++w2) r += RED[(w2 * 8 + wave) * 64 + lane];
; __global__ void __launch_bounds__(512, 2) mega(Params p) {
;     ...
;                 const size_t r = MP + 16 * wave + fr; const int c = n0 + 4 * fq;
;                 const f32x4 x2 = bf4_to_f32(*(const u32x2*)((const bf16_t*)(ws + WS_X1) + r * DM + c)) + a1;
;                 *(u32x2*)((bf16_t*)(ws + WS_X2B) + r * DM + c) = f32_to_bf4(x2); }
	v_mfma_f32_16x16x32_bf16 v[32:35], v[164:167], v[168:171], v[32:35]
	v_mfma_f32_16x16x32_bf16 v[36:39], v[164:167], v[172:175], v[36:39]
	v_mfma_f32_16x16x32_bf16 v[40:43], v[164:167], v[176:179], v[40:43]
	v_mfma_f32_16x16x32_bf16 v[44:47], v[164:167], v[180:183], v[44:47]
	global_load_dwordx4 v[164:167], v14, s[92:93] offset:1344
	global_load_dwordx4 v[168:171], v10, s[90:91] offset:1344
	global_load_dwordx4 v[172:175], v11, s[90:91] offset:1344
	global_load_dwordx4 v[176:179], v12, s[90:91] offset:1344
	global_load_dwordx4 v[180:183], v13, s[90:91] offset:1344
	s_waitcnt vmcnt(35)
	v_mfma_f32_16x16x32_bf16 v[32:35], v[184:187], v[188:191], v[32:35]
	v_mfma_f32_16x16x32_bf16 v[36:39], v[184:187], v[192:195], v[36:39]
	v_mfma_f32_16x16x32_bf16 v[40:43], v[184:187], v[196:199], v[40:43]
	v_mfma_f32_16x16x32_bf16 v[44:47], v[184:187], v[200:203], v[44:47]
	s_waitcnt vmcnt(30)
	v_mfma_f32_16x16x32_bf16 v[32:35], v[204:207], v[208:211], v[32:35]
	v_mfma_f32_16x16x32_bf16 v[36:39], v[204:207], v[212:215], v[36:39]
	v_mfma_f32_16x16x32_bf16 v[40:43], v[204:207], v[216:219], v[40:43]
	v_mfma_f32_16x16x32_bf16 v[44:47], v[204:207], v[220:223], v[44:47]
	s_waitcnt vmcnt(25)
	v_mfma_f32_16x16x32_bf16 v[32:35], v[64:67], v[68:71], v[32:35]
	v_mfma_f32_16x16x32_bf16 v[36:39], v[64:67], v[72:75], v[36:39]
	v_mfma_f32_16x16x32_bf16 v[40:43], v[64:67], v[76:79], v[40:43]
	v_mfma_f32_16x16x32_bf16 v[44:47], v[64:67], v[80:83], v[44:47]
	s_waitcnt vmcnt(20)
	v_mfma_f32_16x16x32_bf16 v[32:35], v[84:87], v[88:91], v[32:35]
	v_mfma_f32_16x16x32_bf16 v[36:39], v[84:87], v[92:95], v[36:39]
	v_mfma_f32_16x16x32_bf16 v[40:43], v[84:87], v[96:99], v[40:43]
	v_mfma_f32_16x16x32_bf16 v[44:47], v[84:87], v[100:103], v[44:47]
	s_waitcnt vmcnt(15)
	v_mfma_f32_16x16x32_bf16 v[32:35], v[104:107], v[108:111], v[32:35]
	v_mfma_f32_16x16x32_bf16 v[36:39], v[104:107], v[112:115], v[36:39]
	v_mfma_f32_16x16x32_bf16 v[40:43], v[104:107], v[116:119], v[40:43]
	v_mfma_f32_16x16x32_bf16 v[44:47], v[104:107], v[120:123], v[44:47]
	s_waitcnt vmcnt(10)
	v_mfma_f32_16x16x32_bf16 v[32:35], v[124:127], v[128:131], v[32:35]
	v_mfma_f32_16x16x32_bf16 v[36:39], v[124:127], v[132:135], v[36:39]
	v_mfma_f32_16x16x32_bf16 v[40:43], v[124:127], v[136:139], v[40:43]
	v_mfma_f32_16x16x32_bf16 v[44:47], v[124:127], v[140:143], v[44:47]
	s_waitcnt vmcnt(5)
	v_mfma_f32_16x16x32_bf16 v[32:35], v[144:147], v[148:151], v[32:35]
	v_mfma_f32_16x16x32_bf16 v[36:39], v[144:147], v[152:155], v[36:39]
	v_mfma_f32_16x16x32_bf16 v[40:43], v[144:147], v[156:159], v[40:43]
	v_mfma_f32_16x16x32_bf16 v[44:47], v[144:147], v[160:163], v[44:47]
	s_waitcnt vmcnt(0)
	v_mfma_f32_16x16x32_bf16 v[32:35], v[164:167], v[168:171], v[32:35]
	v_mfma_f32_16x16x32_bf16 v[36:39], v[164:167], v[172:175], v[36:39]
	v_mfma_f32_16x16x32_bf16 v[40:43], v[164:167], v[176:179], v[40:43]
	v_mfma_f32_16x16x32_bf16 v[44:47], v[164:167], v[180:183], v[44:47]
	s_nop 7
	s_nop 3
	ds_write_b128 v20, v[32:35]
	ds_write_b128 v20, v[36:39] offset:1024
	ds_write_b128 v20, v[40:43] offset:2048
	ds_write_b128 v20, v[44:47] offset:3072
	s_waitcnt lgkmcnt(0)
	s_barrier
	s_cmp_gt_u32 s84, 3
	s_cbranch_scc1 .Lmini8_done
	ds_read_b128 v[64:67], v21
	ds_read_b128 v[68:71], v21 offset:4096
	ds_read_b128 v[72:75], v21 offset:8192
	ds_read_b128 v[76:79], v21 offset:12288
	ds_read_b128 v[80:83], v21 offset:16384
	ds_read_b128 v[84:87], v21 offset:20480
	ds_read_b128 v[88:91], v21 offset:24576
	ds_read_b128 v[92:95], v21 offset:28672
	s_waitcnt vmcnt(0) lgkmcnt(0)
	v_add_f32_e32 v64, v64, v68
	v_add_f32_e32 v65, v65, v69
	v_add_f32_e32 v66, v66, v70
	v_add_f32_e32 v67, v67, v71
	v_add_f32_e32 v64, v64, v72
	v_add_f32_e32 v65, v65, v73
	v_add_f32_e32 v66, v66, v74
	v_add_f32_e32 v67, v67, v75
	v_add_f32_e32 v64, v64, v76
	v_add_f32_e32 v65, v65, v77
	v_add_f32_e32 v66, v66, v78
	v_add_f32_e32 v67, v67, v79
	v_add_f32_e32 v64, v64, v80
	v_add_f32_e32 v65, v65, v81
	v_add_f32_e32 v66, v66, v82
	v_add_f32_e32 v67, v67, v83
	v_add_f32_e32 v64, v64, v84
	v_add_f32_e32 v65, v65, v85
	v_add_f32_e32 v66, v66, v86
	v_add_f32_e32 v67, v67, v87
	v_add_f32_e32 v64, v64, v88
	v_add_f32_e32 v65, v65, v89
	v_add_f32_e32 v66, v66, v90
	v_add_f32_e32 v67, v67, v91
	v_add_f32_e32 v64, v64, v92
	v_add_f32_e32 v65, v65, v93
	v_add_f32_e32 v66, v66, v94
	v_add_f32_e32 v67, v67, v95
	v_lshlrev_b32_e32 v228, 16, v224
	v_and_b32_e32 v229, 0xffff0000, v224
	v_lshlrev_b32_e32 v230, 16, v225
	v_and_b32_e32 v231, 0xffff0000, v225
	v_add_f32_e32 v236, v228, v64
	v_add_f32_e32 v237, v229, v65
	v_add_f32_e32 v238, v230, v66
	v_add_f32_e32 v239, v231, v67
	v_cvt_pk_bf16_f32 v244, v236, v237
	v_cvt_pk_bf16_f32 v245, v238, v239
	global_store_dwordx2 v7, v[244:245], s[12:13]
.Lmini8_done:
.LBB0_1300:
	s_cmp_gt_i32 s19, 9
	s_cselect_b64 s[0:1], -1, 0
	s_and_b64 s[4:5], s[6:7], s[0:1]
	s_andn2_b64 vcc, exec, s[4:5]
	s_cbranch_vccnz .LBB0_1331
	s_waitcnt vmcnt(0)
	s_waitcnt vmcnt(0)
	s_barrier
	s_mov_b32 s3, 0
	s_nop 0
	v_mbcnt_lo_u32_b32 v0, -1, s3
	v_mbcnt_hi_u32_b32 v0, -1, v0
	v_or_b32_e32 v0, s24, v0
	s_nop 0
	v_cmp_eq_u32_e32 vcc, 0, v0
	s_and_saveexec_b64 s[4:5], vcc
	s_cbranch_execz .LBB0_1330
	s_add_i32 s6, 0, 0x23ff0
	v_mov_b32_e32 v0, s6
	s_waitcnt vmcnt(0) expcnt(0) lgkmcnt(0)
	s_getreg_b32 s3, hwreg(HW_REG_XCC_ID, 0, 4)
	ds_read_b32 v1, v0
	s_add_i32 s6, 0, 0x23ff4
	v_mov_b32_e32 v0, s6
	ds_read_b32 v0, v0
	s_and_b32 s3, s3, 15
	s_waitcnt lgkmcnt(1)
	v_cmp_ne_u32_e32 vcc, 0, v1
	s_cbranch_vccnz .LBB0_1308
	s_add_u32 s6, s22, 0x1f32a400
	s_addc_u32 s7, s23, 0
	s_add_u32 s8, s22, 0x1f32a500
	s_addc_u32 s9, s23, 0
	s_add_u32 s10, s22, 0x1f32a600
	s_addc_u32 s11, s23, 0
	s_add_u32 s12, s22, 0x1f32a700
	s_addc_u32 s13, s23, 0
	s_add_u32 s14, s22, 0x1f32a800
	s_addc_u32 s15, s23, 0
	s_add_u32 s16, s22, 0x1f32a900
	s_addc_u32 s17, s23, 0
	s_add_u32 s26, s22, 0x1f32aa00
	s_addc_u32 s27, s23, 0
	s_add_u32 s28, s22, 0x1f32ab00
	s_addc_u32 s29, s23, 0
	s_add_u32 s30, s22, 0x1f32ac00
	s_addc_u32 s31, s23, 0
	s_add_u32 s34, s22, 0x1f32ad00
	s_addc_u32 s35, s23, 0
	s_add_u32 s36, s22, 0x1f32ae00
	s_addc_u32 s37, s23, 0
	s_add_u32 s38, s22, 0x1f32af00
	s_addc_u32 s39, s23, 0
	s_add_u32 s40, s22, 0x1f32b000
	s_addc_u32 s41, s23, 0
	s_add_u32 s42, s22, 0x1f32b100
	s_addc_u32 s43, s23, 0
	s_add_u32 s44, s22, 0x1f32b200
	s_addc_u32 s45, s23, 0
	s_add_u32 s46, s22, 0x1f32b300
	s_addc_u32 s47, s23, 0
	v_mov_b32_e32 v16, 0
	s_branch .LBB0_1305

; #define LAS __attribute__((address_space(3)))
; __device__ __forceinline__ f32x4 mini_acc(const bf16_t* A, int lda, const bf16_t* Bt, int ldb, int K, int n0, int wave, int fr, int fq, LAS unsigned char* lds) {
;     asm volatile("" : "+s"(lda), "+s"(ldb));
;     const int lane = fq * 16 + fr, ks = K >> 3;
;     const bf16_t* ap = A + (size_t)(MP + fr) * lda + wave * ks + 8 * fq;
;     const bf16_t* bp = Bt + (size_t)(n0 + fr) * ldb + wave * ks + 8 * fq;
;     f32x4 acc[8];
; #pragma unroll
;     for (int m = 0; m < 8; ++m) acc[m] = (f32x4){0.f, 0.f, 0.f, 0.f};
;     for (int k = 0; k < ks; k += 64) {
;         const bool two = (k + 32 < ks);
;         bf16x8 bq[2], aq[2][8];
;         bq[0] = *(const bf16x8*)(bp + k);
; #pragma unroll
;         for (int m = 0; m < 8; ++m) aq[0][m] = *(const bf16x8*)(ap + (size_t)(16 * m) * lda + k);
;         if (two) { bq[1] = *(const bf16x8*)(bp + k + 32);
; #pragma unroll
;             for (int m = 0; m < 8; ++m) aq[1][m] = *(const bf16x8*)(ap + (size_t)(16 * m) * lda + k + 32); }
; #pragma unroll
;         for (int m = 0; m < 8; ++m) acc[m] = __builtin_amdgcn_mfma_f32_16x16x32_bf16(bq[0], aq[0][m], acc[m], 0, 0, 0);
;         if (two) {
; #pragma unroll
;             for (int m = 0; m < 8; ++m) acc[m] = __builtin_amdgcn_mfma_f32_16x16x32_bf16(bq[1], aq[1][m], acc[m], 0, 0, 0); }
; __global__ void __launch_bounds__(512, 2) mega(Params p) {
;     ...
;         {
;             const int tid = opaque_tid(wave_s), lane = tid & 63, wave = tid >> 6, fr = lane & 15, fq = lane >> 4;
;             for (int nt = bx; nt < 128; nt += G) { const int n0 = nt * 16; const f32x4 z4 = (f32x4){0.f, 0.f, 0.f, 0.f};
;                 const f32x4 a1 = mini_acc((const bf16_t*)(ws + WS_PBF), 256, (const bf16_t*)(ws + WS_WPLE), 256, 256, n0, wave, fr, fq, lds);
;                 const f32x4 a2 = mini_acc((const bf16_t*)(ws + WS_X2B), DM, (const bf16_t*)(ws + WS_WPLEG), DM, DM, n0, wave, fr, fq, lds);
.LBB0_1378:
	s_mov_b64 exec, -1
	s_cmpk_gt_u32 s2, 0xff
	s_cbranch_scc1 .Lmini9_done
	v_mbcnt_lo_u32_b32 v0, -1, 0
	v_mbcnt_hi_u32_b32 v0, -1, v0
	v_and_b32_e32 v1, 15, v0
	v_lshrrev_b32_e32 v2, 4, v0
	s_lshr_b32 s84, s24, 6
	s_and_b32 s85, s2, 7
	s_lshr_b32 s86, s2, 4
	s_lshl_b32 s86, s86, 3
	s_or_b32 s85, s85, s86
	s_lshl_b32 s85, s85, 4
	s_bfe_u32 s86, s2, 0x10003
	s_lshl_b32 s86, s86, 6
	s_addk_i32 s86, 0x2000
	v_lshlrev_b32_e32 v20, 4, v0
	s_lshl_b32 s87, s84, 12
	v_add_u32_e32 v20, s87, v20
	v_lshlrev_b32_e32 v21, 4, v0
	s_lshl_b32 s87, s84, 10
	v_add_u32_e32 v21, s87, v21
	s_add_u32 s90, s22, 0x5f80000
	s_addc_u32 s91, s23, 0
	s_add_u32 s92, s22, 0x5680000
	s_addc_u32 s93, s23, 0
	s_mul_i32 s87, s84, 0x40
	v_lshl_add_u32 v3, v2, 4, s87
	v_add_u32_e32 v4, s86, v1
	s_mov_b32 s88, 0x200
	v_mul_lo_u32 v5, v4, s88
	v_add_u32_e32 v10, v5, v3
	v_add_u32_e32 v11, 0x2000, v10
	v_add_u32_e32 v12, 0x4000, v10
	v_add_u32_e32 v13, 0x6000, v10
	v_add_u32_e32 v4, s85, v1
	s_mov_b32 s88, 0x200
	v_mul_lo_u32 v5, v4, s88
	v_add_u32_e32 v14, v5, v3
	s_add_u32 s94, s22, 0x85aa000
	s_addc_u32 s95, s23, 0
	s_add_u32 s96, s22, 0x5780000
	s_addc_u32 s97, s23, 0
	s_mul_i32 s87, s84, 0x200
	v_lshl_add_u32 v3, v2, 4, s87
	v_add_u32_e32 v4, s86, v1
	s_mov_b32 s88, 0x1000
	v_mul_lo_u32 v5, v4, s88
	v_add_u32_e32 v15, v5, v3
	v_add_u32_e32 v16, 0x10000, v15
	v_add_u32_e32 v17, 0x20000, v15
	v_add_u32_e32 v18, 0x30000, v15
	v_add_u32_e32 v4, s85, v1
	s_mov_b32 s88, 0x1000
	v_mul_lo_u32 v5, v4, s88
	v_add_u32_e32 v19, v5, v3
	v_mov_b32_e32 v32, 0
	v_mov_b32_e32 v33, 0
	v_mov_b32_e32 v34, 0
	v_mov_b32_e32 v35, 0
	v_mov_b32_e32 v36, 0
	v_mov_b32_e32 v37, 0
	v_mov_b32_e32 v38, 0
	v_mov_b32_e32 v39, 0
	v_mov_b32_e32 v40, 0
	v_mov_b32_e32 v41, 0
	v_mov_b32_e32 v42, 0
	v_mov_b32_e32 v43, 0
	v_mov_b32_e32 v44, 0
	v_mov_b32_e32 v45, 0
	v_mov_b32_e32 v46, 0
	v_mov_b32_e32 v47, 0
	v_mov_b32_e32 v48, 0
	v_mov_b32_e32 v49, 0
	v_mov_b32_e32 v50, 0
	v_mov_b32_e32 v51, 0
	v_mov_b32_e32 v52, 0
	v_mov_b32_e32 v53, 0
	v_mov_b32_e32 v54, 0
	v_mov_b32_e32 v55, 0
	v_mov_b32_e32 v56, 0
	v_mov_b32_e32 v57, 0
	v_mov_b32_e32 v58, 0
	v_mov_b32_e32 v59, 0
	v_mov_b32_e32 v60, 0
	v_mov_b32_e32 v61, 0
	v_mov_b32_e32 v62, 0
	v_mov_b32_e32 v63, 0
	s_cmp_gt_u32 s84, 3
	s_cbranch_scc1 .Lmini9_noepi
	s_lshl_b32 s87, s84, 4
	s_add_i32 s87, s87, s86
	v_add_u32_e32 v4, s87, v1
	v_lshl_add_u32 v5, v2, 2, s85
	v_lshlrev_b32_e32 v7, 12, v4
	v_lshl_add_u32 v7, v5, 1, v7
	s_add_u32 s8, s22, 0x85aa000
	s_addc_u32 s9, s23, 0
	s_add_u32 s12, s22, 0x17d2a000
	s_addc_u32 s13, s23, 0
	global_load_dwordx2 v[224:225], v7, s[8:9]
.Lmini9_noepi:
	global_load_dwordx4 v[64:67], v14, s[92:93]
	global_load_dwordx4 v[68:71], v10, s[90:91]
	global_load_dwordx4 v[72:75], v11, s[90:91]
	global_load_dwordx4 v[76:79], v12, s[90:91]
	global_load_dwordx4 v[80:83], v13, s[90:91]
	global_load_dwordx4 v[84:87], v19, s[96:97]
	global_load_dwordx4 v[88:91], v15, s[94:95]
	global_load_dwordx4 v[92:95], v16, s[94:95]
	global_load_dwordx4 v[96:99], v17, s[94:95]
	global_load_dwordx4 v[100:103], v18, s[94:95]
	global_load_dwordx4 v[104:107], v19, s[96:97] offset:64
	global_load_dwordx4 v[108:111], v15, s[94:95] offset:64
	global_load_dwordx4 v[112:115], v16, s[94:95] offset:64
	global_load_dwordx4 v[116:119], v17, s[94:95] offset:64
	global_load_dwordx4 v[120:123], v18, s[94:95] offset:64
	global_load_dwordx4 v[124:127], v19, s[96:97] offset:128
	global_load_dwordx4 v[128:131], v15, s[94:95] offset:128
	global_load_dwordx4 v[132:135], v16, s[94:95] offset:128
	global_load_dwordx4 v[136:139], v17, s[94:95] offset:128
	global_load_dwordx4 v[140:143], v18, s[94:95] offset:128
	global_load_dwordx4 v[144:147], v19, s[96:97] offset:192
	global_load_dwordx4 v[148:151], v15, s[94:95] offset:192
	global_load_dwordx4 v[152:155], v16, s[94:95] offset:192
	global_load_dwordx4 v[156:159], v17, s[94:95] offset:192
	global_load_dwordx4 v[160:163], v18, s[94:95] offset:192
	global_load_dwordx4 v[164:167], v19, s[96:97] offset:256
	global_load_dwordx4 v[168:171], v15, s[94:95] offset:256
	global_load_dwordx4 v[172:175], v16, s[94:95] offset:256
	global_load_dwordx4 v[176:179], v17, s[94:95] offset:256
	global_load_dwordx4 v[180:183], v18, s[94:95] offset:256
	global_load_dwordx4 v[184:187], v19, s[96:97] offset:320
	global_load_dwordx4 v[188:191], v15, s[94:95] offset:320
	global_load_dwordx4 v[192:195], v16, s[94:95] offset:320
	global_load_dwordx4 v[196:199], v17, s[94:95] offset:320
	global_load_dwordx4 v[200:203], v18, s[94:95] offset:320
	global_load_dwordx4 v[204:207], v19, s[96:97] offset:384
	global_load_dwordx4 v[208:211], v15, s[94:95] offset:384
	global_load_dwordx4 v[212:215], v16, s[94:95] offset:384
	global_load_dwordx4 v[216:219], v17, s[94:95] offset:384
	global_load_dwordx4 v[220:223], v18, s[94:95] offset:384
	s_waitcnt vmcnt(35)
	v_mfma_f32_16x16x32_bf16 v[32:35], v[64:67], v[68:71], v[32:35]
	v_mfma_f32_16x16x32_bf16 v[36:39], v[64:67], v[72:75], v[36:39]
	v_mfma_f32_16x16x32_bf16 v[40:43], v[64:67], v[76:79], v[40:43]
	v_mfma_f32_16x16x32_bf16 v[44:47], v[64:67], v[80:83], v[44:47]
	global_load_dwordx4 v[64:67], v19, s[96:97] offset:448
	global_load_dwordx4 v[68:71], v15, s[94:95] offset:448
	global_load_dwordx4 v[72:75], v16, s[94:95] offset:448
	global_load_dwordx4 v[76:79], v17, s[94:95] offset:448
	global_load_dwordx4 v[80:83], v18, s[94:95] offset:448
	s_waitcnt vmcnt(35)
	v_mfma_f32_16x16x32_bf16 v[48:51], v[84:87], v[88:91], v[48:51]
	v_mfma_f32_16x16x32_bf16 v[52:55], v[84:87], v[92:95], v[52:55]
	v_mfma_f32_16x16x32_bf16 v[56:59], v[84:87], v[96:99], v[56:59]
	v_mfma_f32_16x16x32_bf16 v[60:63], v[84:87], v[100:103], v[60:63]
	s_waitcnt vmcnt(30)
; #define LAS __attribute__((address_space(3)))
; __device__ __forceinline__ float sigmoidf_(float x) { return __builtin_amdgcn_rcpf(1.0f + __expf(-x)); }
; #define BAR_LDS() do { asm volatile("s_waitcnt lgkmcnt(0)" ::: "memory"); __builtin_amdgcn_s_barrier(); asm volatile("" ::: "memory"); } while (0)
; __device__ __forceinline__ f32x4 bf4_to_f32(u32x2 w) { return (f32x4){bflo(w.x), bfhi(w.x), bflo(w.y), bfhi(w.y)}; }
; __device__ __forceinline__ u32x2 f32_to_bf4(f32x4 v) { u32x2 w; w.x = pk2(v[0], v[1]); w.y = pk2(v[2], v[3]); return w; }
; __device__ __forceinline__ f32x4 mini_acc(const bf16_t* A, int lda, const bf16_t* Bt, int ldb, int K, int n0, int wave, int fr, int fq, LAS unsigned char* lds) {
;     ...
;     for (int k = 0; k < ks; k += 64) {
;         const bool two = (k + 32 < ks);
;         bf16x8 bq[2], aq[2][8];
;         bq[0] = *(const bf16x8*)(bp + k);
; #pragma unroll
;         for (int m = 0; m < 8; ++m) aq[0][m] = *(const bf16x8*)(ap + (size_t)(16 * m) * lda + k);
;         if (two) { bq[1] = *(const bf16x8*)(bp + k + 32);
; #pragma unroll
;             for (int m = 0; m < 8; ++m) aq[1][m] = *(const bf16x8*)(ap + (size_t)(16 * m) * lda + k + 32); }
; #pragma unroll
;         for (int m = 0; m < 8; ++m) acc[m] = __builtin_amdgcn_mfma_f32_16x16x32_bf16(bq[0], aq[0][m], acc[m], 0, 0, 0);
;         if (two) {
; #pragma unroll
;             for (int m = 0; m < 8; ++m) acc[m] = __builtin_amdgcn_mfma_f32_16x16x32_bf16(bq[1], aq[1][m], acc[m], 0, 0, 0); }
;     }
;     LAS f32x4* RED = (LAS f32x4*)lds;
; #pragma unroll
;     for (int m = 0; m < 8; ++m) RED[(wave * 8 + m) * 64 + lane] = acc[m];
;     BAR_LDS();
;     f32x4 r = (f32x4){0.f, 0.f, 0.f, 0.f};
; #pragma unroll
;     for (int w2 = 0; w2 < 8; ++w2) r += RED[(w2 * 8 + wave) * 64 + lane];
; __global__ void __launch_bounds__(512, 2) mega(Params p) {
;     ...
;                 const size_t r = MP + 16 * wave + fr; const int c = n0 + 4 * fq;
;                 f32x4 x3 = bf4_to_f32(*(const u32x2*)((const bf16_t*)(ws + WS_X2B) + r * DM + c));
; #pragma unroll
;                 for (int j = 0; j < 4; ++j) x3[j] += a1[j] * sigmoidf_(a2[j]);
;                 *(u32x2*)((bf16_t*)(ws + WS_X1) + r * DM + c) = f32_to_bf4(x3); }
	v_mfma_f32_16x16x32_bf16 v[48:51], v[104:107], v[108:111], v[48:51]
	v_mfma_f32_16x16x32_bf16 v[52:55], v[104:107], v[112:115], v[52:55]
	v_mfma_f32_16x16x32_bf16 v[56:59], v[104:107], v[116:119], v[56:59]
	v_mfma_f32_16x16x32_bf16 v[60:63], v[104:107], v[120:123], v[60:63]
	s_waitcnt vmcnt(25)
	v_mfma_f32_16x16x32_bf16 v[48:51], v[124:127], v[128:131], v[48:51]
	v_mfma_f32_16x16x32_bf16 v[52:55], v[124:127], v[132:135], v[52:55]
	v_mfma_f32_16x16x32_bf16 v[56:59], v[124:127], v[136:139], v[56:59]
	v_mfma_f32_16x16x32_bf16 v[60:63], v[124:127], v[140:143], v[60:63]
	s_waitcnt vmcnt(20)
	v_mfma_f32_16x16x32_bf16 v[48:51], v[144:147], v[148:151], v[48:51]
	v_mfma_f32_16x16x32_bf16 v[52:55], v[144:147], v[152:155], v[52:55]
	v_mfma_f32_16x16x32_bf16 v[56:59], v[144:147], v[156:159], v[56:59]
	v_mfma_f32_16x16x32_bf16 v[60:63], v[144:147], v[160:163], v[60:63]
	s_waitcnt vmcnt(15)
	v_mfma_f32_16x16x32_bf16 v[48:51], v[164:167], v[168:171], v[48:51]
	v_mfma_f32_16x16x32_bf16 v[52:55], v[164:167], v[172:175], v[52:55]
	v_mfma_f32_16x16x32_bf16 v[56:59], v[164:167], v[176:179], v[56:59]
	v_mfma_f32_16x16x32_bf16 v[60:63], v[164:167], v[180:183], v[60:63]
	s_waitcnt vmcnt(10)
	v_mfma_f32_16x16x32_bf16 v[48:51], v[184:187], v[188:191], v[48:51]
	v_mfma_f32_16x16x32_bf16 v[52:55], v[184:187], v[192:195], v[52:55]
	v_mfma_f32_16x16x32_bf16 v[56:59], v[184:187], v[196:199], v[56:59]
	v_mfma_f32_16x16x32_bf16 v[60:63], v[184:187], v[200:203], v[60:63]
	s_waitcnt vmcnt(5)
	v_mfma_f32_16x16x32_bf16 v[48:51], v[204:207], v[208:211], v[48:51]
	v_mfma_f32_16x16x32_bf16 v[52:55], v[204:207], v[212:215], v[52:55]
	v_mfma_f32_16x16x32_bf16 v[56:59], v[204:207], v[216:219], v[56:59]
	v_mfma_f32_16x16x32_bf16 v[60:63], v[204:207], v[220:223], v[60:63]
	s_waitcnt vmcnt(0)
	v_mfma_f32_16x16x32_bf16 v[48:51], v[64:67], v[68:71], v[48:51]
	v_mfma_f32_16x16x32_bf16 v[52:55], v[64:67], v[72:75], v[52:55]
	v_mfma_f32_16x16x32_bf16 v[56:59], v[64:67], v[76:79], v[56:59]
	v_mfma_f32_16x16x32_bf16 v[60:63], v[64:67], v[80:83], v[60:63]
	s_nop 7
	s_nop 3
	ds_write_b128 v20, v[32:35]
	ds_write_b128 v20, v[36:39] offset:1024
	ds_write_b128 v20, v[40:43] offset:2048
	ds_write_b128 v20, v[44:47] offset:3072
	ds_write_b128 v20, v[48:51] offset:32768
	ds_write_b128 v20, v[52:55] offset:33792
	ds_write_b128 v20, v[56:59] offset:34816
	ds_write_b128 v20, v[60:63] offset:35840
	s_waitcnt lgkmcnt(0)
	s_barrier
	s_cmp_gt_u32 s84, 3
	s_cbranch_scc1 .Lmini9_done
	ds_read_b128 v[64:67], v21
	ds_read_b128 v[68:71], v21 offset:4096
	ds_read_b128 v[72:75], v21 offset:8192
	ds_read_b128 v[76:79], v21 offset:12288
	ds_read_b128 v[80:83], v21 offset:16384
	ds_read_b128 v[84:87], v21 offset:20480
	ds_read_b128 v[88:91], v21 offset:24576
	ds_read_b128 v[92:95], v21 offset:28672
	ds_read_b128 v[96:99], v21 offset:32768
	ds_read_b128 v[100:103], v21 offset:36864
	ds_read_b128 v[104:107], v21 offset:40960
	ds_read_b128 v[108:111], v21 offset:45056
	ds_read_b128 v[112:115], v21 offset:49152
	ds_read_b128 v[116:119], v21 offset:53248
	ds_read_b128 v[120:123], v21 offset:57344
	ds_read_b128 v[124:127], v21 offset:61440
	s_waitcnt vmcnt(0) lgkmcnt(0)
	v_add_f32_e32 v64, v64, v68
	v_add_f32_e32 v65, v65, v69
	v_add_f32_e32 v66, v66, v70
	v_add_f32_e32 v67, v67, v71
	v_add_f32_e32 v64, v64, v72
	v_add_f32_e32 v65, v65, v73
	v_add_f32_e32 v66, v66, v74
	v_add_f32_e32 v67, v67, v75
	v_add_f32_e32 v64, v64, v76
	v_add_f32_e32 v65, v65, v77
	v_add_f32_e32 v66, v66, v78
	v_add_f32_e32 v67, v67, v79
	v_add_f32_e32 v64, v64, v80
	v_add_f32_e32 v65, v65, v81
	v_add_f32_e32 v66, v66, v82
	v_add_f32_e32 v67, v67, v83
	v_add_f32_e32 v64, v64, v84
	v_add_f32_e32 v65, v65, v85
	v_add_f32_e32 v66, v66, v86
	v_add_f32_e32 v67, v67, v87
	v_add_f32_e32 v64, v64, v88
	v_add_f32_e32 v65, v65, v89
	v_add_f32_e32 v66, v66, v90
	v_add_f32_e32 v67, v67, v91
	v_add_f32_e32 v64, v64, v92
	v_add_f32_e32 v65, v65, v93
	v_add_f32_e32 v66, v66, v94
	v_add_f32_e32 v67, v67, v95
	v_add_f32_e32 v96, v96, v100
	v_add_f32_e32 v97, v97, v101
	v_add_f32_e32 v98, v98, v102
	v_add_f32_e32 v99, v99, v103
	v_add_f32_e32 v96, v96, v104
	v_add_f32_e32 v97, v97, v105
	v_add_f32_e32 v98, v98, v106
	v_add_f32_e32 v99, v99, v107
	v_add_f32_e32 v96, v96, v108
	v_add_f32_e32 v97, v97, v109
	v_add_f32_e32 v98, v98, v110
	v_add_f32_e32 v99, v99, v111
	v_add_f32_e32 v96, v96, v112
	v_add_f32_e32 v97, v97, v113
	v_add_f32_e32 v98, v98, v114
	v_add_f32_e32 v99, v99, v115
	v_add_f32_e32 v96, v96, v116
	v_add_f32_e32 v97, v97, v117
	v_add_f32_e32 v98, v98, v118
	v_add_f32_e32 v99, v99, v119
	v_add_f32_e32 v96, v96, v120
	v_add_f32_e32 v97, v97, v121
	v_add_f32_e32 v98, v98, v122
	v_add_f32_e32 v99, v99, v123
	v_add_f32_e32 v96, v96, v124
	v_add_f32_e32 v97, v97, v125
	v_add_f32_e32 v98, v98, v126
	v_add_f32_e32 v99, v99, v127
	v_lshlrev_b32_e32 v228, 16, v224
	v_and_b32_e32 v229, 0xffff0000, v224
	v_lshlrev_b32_e32 v230, 16, v225
	v_and_b32_e32 v231, 0xffff0000, v225
	v_mul_f32_e32 v240, 0xbfb8aa3b, v96
	v_mul_f32_e32 v241, 0xbfb8aa3b, v97
	v_mul_f32_e32 v242, 0xbfb8aa3b, v98
	v_mul_f32_e32 v243, 0xbfb8aa3b, v99
	v_exp_f32_e32 v240, v240
	v_exp_f32_e32 v241, v241
	v_exp_f32_e32 v242, v242
	v_exp_f32_e32 v243, v243
	s_nop 0
	v_add_f32_e32 v240, 1.0, v240
	v_add_f32_e32 v241, 1.0, v241
	v_add_f32_e32 v242, 1.0, v242
	v_add_f32_e32 v243, 1.0, v243
	v_rcp_f32_e32 v240, v240
	v_rcp_f32_e32 v241, v241
	v_rcp_f32_e32 v242, v242
	v_rcp_f32_e32 v243, v243
	s_nop 0
	v_fma_f32 v236, v64, v240, v228
	v_fma_f32 v237, v65, v241, v229
	v_fma_f32 v238, v66, v242, v230
	v_fma_f32 v239, v67, v243, v231
	v_cvt_pk_bf16_f32 v244, v236, v237
	v_cvt_pk_bf16_f32 v245, v238, v239
	global_store_dwordx2 v7, v[244:245], s[12:13]
; #define LAS __attribute__((address_space(3)))
; __device__ __forceinline__ unsigned xb_ld(unsigned* p)              { return __hip_atomic_load(p, __ATOMIC_RELAXED, __HIP_MEMORY_SCOPE_AGENT); }
; __device__ __forceinline__ unsigned xb_xcc_id() { return (unsigned)__builtin_amdgcn_s_getreg((3 << 11) | 20) & 0xFu; }
; __device__ __forceinline__ void xcd_barrier(unsigned* bar, volatile LAS unsigned* st, int wave_s) {
;     asm volatile("s_waitcnt vmcnt(0)" ::: "memory");
;     __syncthreads();
;     if (opaque_tid(wave_s) == 0) {
;         __builtin_amdgcn_s_waitcnt(0);
;         const unsigned x = xb_xcc_id();
;         unsigned nloc = st[0], nx = st[1];
;         if (nloc == 0u) {
;             const unsigned G = gridDim.x; unsigned sum, cnt, mine;
;             for (;;) { sum = 0u; cnt = 0u; mine = 0u;
; #pragma unroll
;                 for (unsigned j = 0; j < 16; ++j) { const unsigned c = xb_ld(&bar[XB_XCNT(j)]); sum += c; cnt += (c > 0u) ? 1u : 0u; mine = (j == x) ? c : mine; }
;                 if (sum == G) break;
;                 __builtin_amdgcn_s_sleep(1); }
;             nloc = mine > 0u ? mine : 1u; nx = cnt > 0u ? cnt : 1u; st[0] = nloc; st[1] = nx; }
.Lmini9_done:
.LBB0_1381:
	s_cmp_gt_i32 s19, 10
	s_cselect_b64 s[0:1], -1, 0
	s_and_b64 s[4:5], s[4:5], s[0:1]
	s_andn2_b64 vcc, exec, s[4:5]
	s_cbranch_vccnz .LBB0_1412
	s_waitcnt vmcnt(0)
	s_waitcnt vmcnt(0)
	s_barrier
	s_mov_b32 s3, 0
	s_nop 0
	v_mbcnt_lo_u32_b32 v0, -1, s3
	v_mbcnt_hi_u32_b32 v0, -1, v0
	v_or_b32_e32 v0, s24, v0
	s_nop 0
	v_cmp_eq_u32_e32 vcc, 0, v0
	s_and_saveexec_b64 s[4:5], vcc
	s_cbranch_execz .LBB0_1411
	s_add_i32 s6, 0, 0x23ff0
	v_mov_b32_e32 v0, s6
	s_waitcnt vmcnt(0) expcnt(0) lgkmcnt(0)
	s_getreg_b32 s3, hwreg(HW_REG_XCC_ID, 0, 4)
	ds_read_b32 v1, v0
	s_add_i32 s6, 0, 0x23ff4
	v_mov_b32_e32 v0, s6
	ds_read_b32 v0, v0
	s_and_b32 s3, s3, 15
	s_waitcnt lgkmcnt(1)
	v_cmp_ne_u32_e32 vcc, 0, v1
	s_cbranch_vccnz .LBB0_1389
	s_add_u32 s6, s22, 0x1f32a400
	s_addc_u32 s7, s23, 0
	s_add_u32 s8, s22, 0x1f32a500
	s_addc_u32 s9, s23, 0
	s_add_u32 s10, s22, 0x1f32a600
	s_addc_u32 s11, s23, 0
	s_add_u32 s12, s22, 0x1f32a700
	s_addc_u32 s13, s23, 0
	s_add_u32 s14, s22, 0x1f32a800
	s_addc_u32 s15, s23, 0
	s_add_u32 s16, s22, 0x1f32a900
	s_addc_u32 s17, s23, 0
	s_add_u32 s26, s22, 0x1f32aa00
	s_addc_u32 s27, s23, 0
	s_add_u32 s28, s22, 0x1f32ab00
	s_addc_u32 s29, s23, 0
	s_add_u32 s30, s22, 0x1f32ac00
	s_addc_u32 s31, s23, 0
	s_add_u32 s34, s22, 0x1f32ad00
	s_addc_u32 s35, s23, 0
	s_add_u32 s36, s22, 0x1f32ae00
	s_addc_u32 s37, s23, 0
	s_add_u32 s38, s22, 0x1f32af00
	s_addc_u32 s39, s23, 0
	s_add_u32 s40, s22, 0x1f32b000
	s_addc_u32 s41, s23, 0
	s_add_u32 s42, s22, 0x1f32b100
	s_addc_u32 s43, s23, 0
	s_add_u32 s44, s22, 0x1f32b200
	s_addc_u32 s45, s23, 0
	s_add_u32 s46, s22, 0x1f32b300
	s_addc_u32 s47, s23, 0
	v_mov_b32_e32 v16, 0
	s_branch .LBB0_1386
